# E47: snake block order with the k order alternating per accumulator, so the fragment shared by neighbouring accumulators is used by adjacent MFMAs (f32 sum order of the two k-steps swapped for every o
# speedup vs baseline: 1.0002x; 1.0002x over previous
.Lcm1_skip:
.LBB0_225:
	ds_read_b128 v[128:131], v157
	ds_read_b128 v[132:135], v157 offset:1024
	ds_read_b128 v[146:149], v157 offset:2048
	ds_read_b128 v[164:167], v157 offset:3072
	ds_read_b128 v[168:171], v159
	ds_read_b128 v[172:175], v159 offset:1024
	ds_read_b128 v[176:179], v159 offset:2048
	ds_read_b128 v[180:183], v159 offset:3072
	s_add_u32 s36, s22, 0xfff80080
	s_addc_u32 s37, s23, -1
	s_cmp_eq_u32 s78, 28
	s_cselect_b32 s81, s5, s37
	s_cselect_b32 s80, s14, s36
	s_cselect_b32 vcc_hi, s20, s45
	s_cselect_b32 vcc_lo, s21, s24
	s_add_i32 m0, s77, 0xc000
	ds_read_b128 v[184:187], v161
	ds_read_b128 v[188:191], v161 offset:1024
	ds_read_b128 v[192:195], v161 offset:2048
	ds_read_b128 v[196:199], v161 offset:3072
	ds_read_b128 v[200:203], v161 offset:4096
	ds_read_b128 v[204:207], v161 offset:5120
	ds_read_b128 v[208:211], v161 offset:6144
	ds_read_b128 v[212:215], v161 offset:7168
	global_load_lds_dwordx4 v140, s[22:23]
	s_add_i32 m0, s77, 0xe000
	s_nop 0
	s_add_u32 s98, s22, s6
	s_addc_u32 s99, s23, s7
	global_load_lds_dwordx4 v140, s[98:99]
	s_waitcnt vmcnt(8)
	s_waitcnt lgkmcnt(0)
	s_barrier
	s_setprio 1
	s_waitcnt lgkmcnt(0)
	v_mfma_i32_16x16x64_i8 v[0:3], v[128:131], v[184:187], v[0:3]
	v_mfma_i32_16x16x64_i8 v[0:3], v[132:135], v[188:191], v[0:3]
	v_mfma_i32_16x16x64_i8 v[56:59], v[164:167], v[188:191], v[56:59]
	v_mfma_i32_16x16x64_i8 v[56:59], v[146:149], v[184:187], v[56:59]
	v_mfma_i32_16x16x64_i8 v[88:91], v[168:171], v[184:187], v[88:91]
	v_mfma_i32_16x16x64_i8 v[88:91], v[172:175], v[188:191], v[88:91]
	v_mfma_i32_16x16x64_i8 v[120:123], v[180:183], v[188:191], v[120:123]
	v_mfma_i32_16x16x64_i8 v[120:123], v[176:179], v[184:187], v[120:123]
	v_mfma_i32_16x16x64_i8 v[116:119], v[176:179], v[192:195], v[116:119]
	v_mfma_i32_16x16x64_i8 v[116:119], v[180:183], v[196:199], v[116:119]
	v_mfma_i32_16x16x64_i8 v[84:87], v[172:175], v[196:199], v[84:87]
	v_mfma_i32_16x16x64_i8 v[84:87], v[168:171], v[192:195], v[84:87]
	v_mfma_i32_16x16x64_i8 v[52:55], v[146:149], v[192:195], v[52:55]
	v_mfma_i32_16x16x64_i8 v[52:55], v[164:167], v[196:199], v[52:55]
	v_mfma_i32_16x16x64_i8 v[4:7], v[132:135], v[196:199], v[4:7]
	v_mfma_i32_16x16x64_i8 v[4:7], v[128:131], v[192:195], v[4:7]
	s_setprio 0
	s_setprio 1
	v_mfma_i32_16x16x64_i8 v[12:15], v[128:131], v[200:203], v[12:15]
	v_mfma_i32_16x16x64_i8 v[12:15], v[132:135], v[204:207], v[12:15]
	v_mfma_i32_16x16x64_i8 v[48:51], v[164:167], v[204:207], v[48:51]
	v_mfma_i32_16x16x64_i8 v[48:51], v[146:149], v[200:203], v[48:51]
	v_mfma_i32_16x16x64_i8 v[80:83], v[168:171], v[200:203], v[80:83]
	v_mfma_i32_16x16x64_i8 v[80:83], v[172:175], v[204:207], v[80:83]
	v_mfma_i32_16x16x64_i8 v[112:115], v[180:183], v[204:207], v[112:115]
	v_mfma_i32_16x16x64_i8 v[112:115], v[176:179], v[200:203], v[112:115]
	v_mfma_i32_16x16x64_i8 v[108:111], v[176:179], v[208:211], v[108:111]
	v_mfma_i32_16x16x64_i8 v[108:111], v[180:183], v[212:215], v[108:111]
	v_mfma_i32_16x16x64_i8 v[76:79], v[172:175], v[212:215], v[76:79]
	v_mfma_i32_16x16x64_i8 v[76:79], v[168:171], v[208:211], v[76:79]
	s_setprio 2
	s_barrier
	v_mfma_i32_16x16x64_i8 v[44:47], v[146:149], v[208:211], v[44:47]
	v_mfma_i32_16x16x64_i8 v[44:47], v[164:167], v[212:215], v[44:47]
	v_mfma_i32_16x16x64_i8 v[8:11], v[132:135], v[212:215], v[8:11]
	v_mfma_i32_16x16x64_i8 v[8:11], v[128:131], v[208:211], v[8:11]
	s_setprio 0
	s_add_i32 s36, s86, s63
	s_mov_b32 m0, s36
	ds_read_b128 v[184:187], v161 offset:16384
	ds_read_b128 v[188:191], v161 offset:17408
	ds_read_b128 v[192:195], v161 offset:18432
	ds_read_b128 v[196:199], v161 offset:19456
	ds_read_b128 v[200:203], v161 offset:20480
	ds_read_b128 v[204:207], v161 offset:21504
	ds_read_b128 v[208:211], v161 offset:22528
	ds_read_b128 v[212:215], v161 offset:23552
	global_load_lds_dwordx4 v138, vcc
	s_add_i32 m0, s36, 0x2000
	s_add_i32 s36, s87, s63
	s_add_u32 s98, vcc_lo, s6
	s_addc_u32 s99, vcc_hi, s7
	global_load_lds_dwordx4 v138, s[98:99]
	s_mov_b32 m0, s36
	s_nop 0
	s_add_u32 s98, vcc_lo, s8
	s_addc_u32 s99, vcc_hi, s9
	global_load_lds_dwordx4 v138, s[98:99]
	s_add_i32 m0, s36, 0x2000
	s_nop 0
	s_add_u32 s98, vcc_lo, s10
	s_addc_u32 s99, vcc_hi, s11
	global_load_lds_dwordx4 v138, s[98:99]
	s_mov_b32 m0, s77
	s_nop 0
	global_load_lds_dwordx4 v136, s[80:81]
	s_mov_b32 m0, s97
	s_nop 0
	s_add_u32 s98, s80, s6
	s_addc_u32 s99, s81, s7
	global_load_lds_dwordx4 v136, s[98:99]
	s_waitcnt vmcnt(8)
	s_waitcnt lgkmcnt(0)
	s_barrier
	s_setprio 1
	s_waitcnt lgkmcnt(0)
	v_mfma_i32_16x16x64_i8 v[20:23], v[128:131], v[184:187], v[20:23]
	v_mfma_i32_16x16x64_i8 v[20:23], v[132:135], v[188:191], v[20:23]
	v_mfma_i32_16x16x64_i8 v[40:43], v[164:167], v[188:191], v[40:43]
	v_mfma_i32_16x16x64_i8 v[40:43], v[146:149], v[184:187], v[40:43]
	v_mfma_i32_16x16x64_i8 v[72:75], v[168:171], v[184:187], v[72:75]
	v_mfma_i32_16x16x64_i8 v[72:75], v[172:175], v[188:191], v[72:75]
	v_mfma_i32_16x16x64_i8 v[104:107], v[180:183], v[188:191], v[104:107]
	v_mfma_i32_16x16x64_i8 v[104:107], v[176:179], v[184:187], v[104:107]
	v_mfma_i32_16x16x64_i8 v[100:103], v[176:179], v[192:195], v[100:103]
	v_mfma_i32_16x16x64_i8 v[100:103], v[180:183], v[196:199], v[100:103]
	v_mfma_i32_16x16x64_i8 v[68:71], v[172:175], v[196:199], v[68:71]
	v_mfma_i32_16x16x64_i8 v[68:71], v[168:171], v[192:195], v[68:71]
	v_mfma_i32_16x16x64_i8 v[36:39], v[146:149], v[192:195], v[36:39]
	v_mfma_i32_16x16x64_i8 v[36:39], v[164:167], v[196:199], v[36:39]
	v_mfma_i32_16x16x64_i8 v[16:19], v[132:135], v[196:199], v[16:19]
	v_mfma_i32_16x16x64_i8 v[16:19], v[128:131], v[192:195], v[16:19]
	s_setprio 0
	s_setprio 1
	v_mfma_i32_16x16x64_i8 v[24:27], v[128:131], v[200:203], v[24:27]
	v_mfma_i32_16x16x64_i8 v[24:27], v[132:135], v[204:207], v[24:27]
	v_mfma_i32_16x16x64_i8 v[32:35], v[164:167], v[204:207], v[32:35]
	v_mfma_i32_16x16x64_i8 v[32:35], v[146:149], v[200:203], v[32:35]
	v_mfma_i32_16x16x64_i8 v[64:67], v[168:171], v[200:203], v[64:67]
	v_mfma_i32_16x16x64_i8 v[64:67], v[172:175], v[204:207], v[64:67]
	v_mfma_i32_16x16x64_i8 v[96:99], v[180:183], v[204:207], v[96:99]
	v_mfma_i32_16x16x64_i8 v[96:99], v[176:179], v[200:203], v[96:99]
	v_mfma_i32_16x16x64_i8 v[124:127], v[176:179], v[208:211], v[124:127]
	v_mfma_i32_16x16x64_i8 v[124:127], v[180:183], v[212:215], v[124:127]
	v_mfma_i32_16x16x64_i8 v[92:95], v[172:175], v[212:215], v[92:95]
	v_mfma_i32_16x16x64_i8 v[92:95], v[168:171], v[208:211], v[92:95]
	s_setprio 2
	s_barrier
	v_mfma_i32_16x16x64_i8 v[60:63], v[146:149], v[208:211], v[60:63]
	v_mfma_i32_16x16x64_i8 v[60:63], v[164:167], v[212:215], v[60:63]
	v_mfma_i32_16x16x64_i8 v[28:31], v[132:135], v[212:215], v[28:31]
	v_mfma_i32_16x16x64_i8 v[28:31], v[128:131], v[208:211], v[28:31]
	s_setprio 0
	s_add_i32 s36, 0, 0x18000
	v_add_u32_e32 v152, s36, v153
	s_add_i32 s37, 0, 0x1c000
	ds_read_b128 v[128:131], v152
	ds_read_b128 v[132:135], v152 offset:1024
	ds_read_b128 v[146:149], v152 offset:2048
	ds_read_b128 v[164:167], v152 offset:3072
	v_add_u32_e32 v152, s37, v153
	ds_read_b128 v[168:171], v152
	ds_read_b128 v[172:175], v152 offset:1024
	ds_read_b128 v[176:179], v152 offset:2048
	ds_read_b128 v[180:183], v152 offset:3072
	s_mov_b32 m0, s33
	ds_read_b128 v[184:187], v161 offset:32768
	ds_read_b128 v[188:191], v161 offset:33792
	ds_read_b128 v[192:195], v161 offset:34816
	ds_read_b128 v[196:199], v161 offset:35840
	ds_read_b128 v[200:203], v161 offset:36864
	ds_read_b128 v[204:207], v161 offset:37888
	ds_read_b128 v[208:211], v161 offset:38912
	ds_read_b128 v[212:215], v161 offset:39936
	s_add_u32 s98, s80, s8
	s_addc_u32 s99, s81, s9
	global_load_lds_dwordx4 v136, s[98:99]
	s_mov_b32 m0, s93
	s_nop 0
	s_add_u32 s98, s80, s10
	s_addc_u32 s99, s81, s11
	global_load_lds_dwordx4 v136, s[98:99]
	s_waitcnt vmcnt(8)
	s_waitcnt lgkmcnt(0)
	s_barrier
	s_setprio 1
	s_waitcnt lgkmcnt(0)
	v_mfma_i32_16x16x64_i8 v[0:3], v[128:131], v[184:187], v[0:3]
	v_mfma_i32_16x16x64_i8 v[0:3], v[132:135], v[188:191], v[0:3]
	v_mfma_i32_16x16x64_i8 v[56:59], v[164:167], v[188:191], v[56:59]
	v_mfma_i32_16x16x64_i8 v[56:59], v[146:149], v[184:187], v[56:59]
	v_mfma_i32_16x16x64_i8 v[88:91], v[168:171], v[184:187], v[88:91]
	v_mfma_i32_16x16x64_i8 v[88:91], v[172:175], v[188:191], v[88:91]
	v_mfma_i32_16x16x64_i8 v[120:123], v[180:183], v[188:191], v[120:123]
	v_mfma_i32_16x16x64_i8 v[120:123], v[176:179], v[184:187], v[120:123]
	v_mfma_i32_16x16x64_i8 v[116:119], v[176:179], v[192:195], v[116:119]
	v_mfma_i32_16x16x64_i8 v[116:119], v[180:183], v[196:199], v[116:119]
	v_mfma_i32_16x16x64_i8 v[84:87], v[172:175], v[196:199], v[84:87]
	v_mfma_i32_16x16x64_i8 v[84:87], v[168:171], v[192:195], v[84:87]
	v_mfma_i32_16x16x64_i8 v[52:55], v[146:149], v[192:195], v[52:55]
	v_mfma_i32_16x16x64_i8 v[52:55], v[164:167], v[196:199], v[52:55]
	v_mfma_i32_16x16x64_i8 v[4:7], v[132:135], v[196:199], v[4:7]
	v_mfma_i32_16x16x64_i8 v[4:7], v[128:131], v[192:195], v[4:7]
	s_setprio 0
	s_setprio 1
	v_mfma_i32_16x16x64_i8 v[12:15], v[128:131], v[200:203], v[12:15]
	v_mfma_i32_16x16x64_i8 v[12:15], v[132:135], v[204:207], v[12:15]
	v_mfma_i32_16x16x64_i8 v[48:51], v[164:167], v[204:207], v[48:51]
	v_mfma_i32_16x16x64_i8 v[48:51], v[146:149], v[200:203], v[48:51]
	v_mfma_i32_16x16x64_i8 v[80:83], v[168:171], v[200:203], v[80:83]
	v_mfma_i32_16x16x64_i8 v[80:83], v[172:175], v[204:207], v[80:83]
	v_mfma_i32_16x16x64_i8 v[112:115], v[180:183], v[204:207], v[112:115]
	v_mfma_i32_16x16x64_i8 v[112:115], v[176:179], v[200:203], v[112:115]
	v_mfma_i32_16x16x64_i8 v[108:111], v[176:179], v[208:211], v[108:111]
	v_mfma_i32_16x16x64_i8 v[108:111], v[180:183], v[212:215], v[108:111]
	v_mfma_i32_16x16x64_i8 v[76:79], v[172:175], v[212:215], v[76:79]
	v_mfma_i32_16x16x64_i8 v[76:79], v[168:171], v[208:211], v[76:79]
	s_setprio 2
	s_barrier
	v_mfma_i32_16x16x64_i8 v[44:47], v[146:149], v[208:211], v[44:47]
	v_mfma_i32_16x16x64_i8 v[44:47], v[164:167], v[212:215], v[44:47]
	v_mfma_i32_16x16x64_i8 v[8:11], v[132:135], v[212:215], v[8:11]
	v_mfma_i32_16x16x64_i8 v[8:11], v[128:131], v[208:211], v[8:11]
	s_setprio 0
	s_add_i32 s36, s36, s63
	s_mov_b32 m0, s36
	ds_read_b128 v[184:187], v161 offset:49152
	ds_read_b128 v[188:191], v161 offset:50176
	ds_read_b128 v[192:195], v161 offset:51200
	ds_read_b128 v[196:199], v161 offset:52224
	ds_read_b128 v[200:203], v161 offset:53248
	ds_read_b128 v[204:207], v161 offset:54272
	ds_read_b128 v[208:211], v161 offset:55296
	ds_read_b128 v[212:215], v161 offset:56320
	s_add_u32 s98, vcc_lo, s46
	s_addc_u32 s99, vcc_hi, s47
	global_load_lds_dwordx4 v138, s[98:99]
	s_add_i32 m0, s36, 0x2000
	s_add_i32 s36, s37, s63
	s_add_u32 s98, vcc_lo, s48
	s_addc_u32 s99, vcc_hi, s49
	global_load_lds_dwordx4 v138, s[98:99]
	s_mov_b32 m0, s36
	s_add_u32 s98, vcc_lo, s54
	s_addc_u32 s99, vcc_hi, s55
	global_load_lds_dwordx4 v138, s[98:99]
	s_add_i32 m0, s36, 0x2000
	s_nop 0
	s_add_u32 s98, vcc_lo, s56
	s_addc_u32 s99, vcc_hi, s57
	global_load_lds_dwordx4 v138, s[98:99]
	s_mov_b32 m0, s95
	s_nop 0
	s_add_u32 s98, s80, s46
	s_addc_u32 s99, s81, s47
	global_load_lds_dwordx4 v136, s[98:99]
	s_mov_b32 m0, s82
	s_nop 0
	s_add_u32 s98, s80, s48
	s_addc_u32 s99, s81, s49
	global_load_lds_dwordx4 v136, s[98:99]
	s_waitcnt vmcnt(8)
	s_waitcnt lgkmcnt(0)
	s_barrier
	s_setprio 1
	s_waitcnt lgkmcnt(0)
	v_mfma_i32_16x16x64_i8 v[20:23], v[128:131], v[184:187], v[20:23]
	v_mfma_i32_16x16x64_i8 v[20:23], v[132:135], v[188:191], v[20:23]
	v_mfma_i32_16x16x64_i8 v[40:43], v[164:167], v[188:191], v[40:43]
	v_mfma_i32_16x16x64_i8 v[40:43], v[146:149], v[184:187], v[40:43]
	v_mfma_i32_16x16x64_i8 v[72:75], v[168:171], v[184:187], v[72:75]
	v_mfma_i32_16x16x64_i8 v[72:75], v[172:175], v[188:191], v[72:75]
	v_mfma_i32_16x16x64_i8 v[104:107], v[180:183], v[188:191], v[104:107]
	v_mfma_i32_16x16x64_i8 v[104:107], v[176:179], v[184:187], v[104:107]
	v_mfma_i32_16x16x64_i8 v[100:103], v[176:179], v[192:195], v[100:103]
	v_mfma_i32_16x16x64_i8 v[100:103], v[180:183], v[196:199], v[100:103]
	v_mfma_i32_16x16x64_i8 v[68:71], v[172:175], v[196:199], v[68:71]
	v_mfma_i32_16x16x64_i8 v[68:71], v[168:171], v[192:195], v[68:71]
	v_mfma_i32_16x16x64_i8 v[36:39], v[146:149], v[192:195], v[36:39]
	v_mfma_i32_16x16x64_i8 v[36:39], v[164:167], v[196:199], v[36:39]
	v_mfma_i32_16x16x64_i8 v[16:19], v[132:135], v[196:199], v[16:19]
	v_mfma_i32_16x16x64_i8 v[16:19], v[128:131], v[192:195], v[16:19]
	s_setprio 0
	s_setprio 1
	v_mfma_i32_16x16x64_i8 v[24:27], v[128:131], v[200:203], v[24:27]
	v_mfma_i32_16x16x64_i8 v[24:27], v[132:135], v[204:207], v[24:27]
	v_mfma_i32_16x16x64_i8 v[32:35], v[164:167], v[204:207], v[32:35]
	v_mfma_i32_16x16x64_i8 v[32:35], v[146:149], v[200:203], v[32:35]
	v_mfma_i32_16x16x64_i8 v[64:67], v[168:171], v[200:203], v[64:67]
	v_mfma_i32_16x16x64_i8 v[64:67], v[172:175], v[204:207], v[64:67]
	v_mfma_i32_16x16x64_i8 v[96:99], v[180:183], v[204:207], v[96:99]
	v_mfma_i32_16x16x64_i8 v[96:99], v[176:179], v[200:203], v[96:99]
	v_mfma_i32_16x16x64_i8 v[124:127], v[176:179], v[208:211], v[124:127]
	v_mfma_i32_16x16x64_i8 v[124:127], v[180:183], v[212:215], v[124:127]
	v_mfma_i32_16x16x64_i8 v[92:95], v[172:175], v[212:215], v[92:95]
	v_mfma_i32_16x16x64_i8 v[92:95], v[168:171], v[208:211], v[92:95]
	s_setprio 2
	s_barrier
	v_mfma_i32_16x16x64_i8 v[60:63], v[146:149], v[208:211], v[60:63]
	v_mfma_i32_16x16x64_i8 v[60:63], v[164:167], v[212:215], v[60:63]
	v_mfma_i32_16x16x64_i8 v[28:31], v[132:135], v[212:215], v[28:31]
	v_mfma_i32_16x16x64_i8 v[28:31], v[128:131], v[208:211], v[28:31]
	s_setprio 0
	s_add_i32 s78, s78, 2
	s_add_u32 s24, s24, 0x100
	s_addc_u32 s45, s45, 0
	s_add_u32 s22, s22, 0x100
	s_addc_u32 s23, s23, 0
	s_cmp_gt_u32 s78, 29
	s_cbranch_scc0 .LBB0_225
	v_readlane_b32 s14, v250, 9
	v_readlane_b32 s15, v250, 10
	s_and_b64 vcc, exec, s[14:15]
	s_cbranch_vccz .LBB0_228
	s_barrier

.LBB0_298:
	ds_read_b128 v[128:131], v153
	ds_read_b128 v[132:135], v153 offset:1024
	ds_read_b128 v[146:149], v153 offset:2048
	ds_read_b128 v[158:161], v153 offset:3072
	ds_read_b128 v[162:165], v154
	ds_read_b128 v[166:169], v154 offset:1024
	ds_read_b128 v[170:173], v154 offset:2048
	ds_read_b128 v[174:177], v154 offset:3072
	s_add_u32 s36, s78, 0xfff00080
	s_addc_u32 s37, s79, -1
	s_cmp_eq_u32 s81, 60
	s_cselect_b32 s97, s5, s37
	s_cselect_b32 s96, s14, s36
	s_cselect_b32 vcc_hi, s20, s80
	s_cselect_b32 vcc_lo, s21, s22
	s_add_i32 m0, s33, 0xc000
	ds_read_b128 v[178:181], v155
	ds_read_b128 v[182:185], v155 offset:1024
	ds_read_b128 v[186:189], v155 offset:2048
	ds_read_b128 v[190:193], v155 offset:3072
	ds_read_b128 v[194:197], v155 offset:4096
	ds_read_b128 v[198:201], v155 offset:5120
	ds_read_b128 v[202:205], v155 offset:6144
	ds_read_b128 v[206:209], v155 offset:7168
	global_load_lds_dwordx4 v140, s[78:79]
	s_add_i32 m0, s33, 0xe000
	s_nop 0
	s_add_u32 s98, s78, s0
	s_addc_u32 s99, s79, s1
	global_load_lds_dwordx4 v140, s[98:99]
	s_waitcnt vmcnt(8)
	s_waitcnt lgkmcnt(0)
	s_barrier
	s_setprio 1
	s_waitcnt lgkmcnt(0)
	v_mfma_f32_16x16x32_bf16 v[124:127], v[128:131], v[178:181], v[124:127]
	v_mfma_f32_16x16x32_bf16 v[124:127], v[132:135], v[182:185], v[124:127]
	v_mfma_f32_16x16x32_bf16 v[120:123], v[158:161], v[182:185], v[120:123]
	v_mfma_f32_16x16x32_bf16 v[120:123], v[146:149], v[178:181], v[120:123]
	v_mfma_f32_16x16x32_bf16 v[116:119], v[162:165], v[178:181], v[116:119]
	v_mfma_f32_16x16x32_bf16 v[116:119], v[166:169], v[182:185], v[116:119]
	v_mfma_f32_16x16x32_bf16 v[104:107], v[174:177], v[182:185], v[104:107]
	v_mfma_f32_16x16x32_bf16 v[104:107], v[170:173], v[178:181], v[104:107]
	v_mfma_f32_16x16x32_bf16 v[88:91], v[170:173], v[186:189], v[88:91]
	v_mfma_f32_16x16x32_bf16 v[88:91], v[174:177], v[190:193], v[88:91]
	v_mfma_f32_16x16x32_bf16 v[96:99], v[166:169], v[190:193], v[96:99]
	v_mfma_f32_16x16x32_bf16 v[96:99], v[162:165], v[186:189], v[96:99]
	v_mfma_f32_16x16x32_bf16 v[108:111], v[146:149], v[186:189], v[108:111]
	v_mfma_f32_16x16x32_bf16 v[108:111], v[158:161], v[190:193], v[108:111]
	v_mfma_f32_16x16x32_bf16 v[112:115], v[132:135], v[190:193], v[112:115]
	v_mfma_f32_16x16x32_bf16 v[112:115], v[128:131], v[186:189], v[112:115]
	s_setprio 0
	s_setprio 1
	v_mfma_f32_16x16x32_bf16 v[100:103], v[128:131], v[194:197], v[100:103]
	v_mfma_f32_16x16x32_bf16 v[100:103], v[132:135], v[198:201], v[100:103]
	v_mfma_f32_16x16x32_bf16 v[92:95], v[158:161], v[198:201], v[92:95]
	v_mfma_f32_16x16x32_bf16 v[92:95], v[146:149], v[194:197], v[92:95]
	v_mfma_f32_16x16x32_bf16 v[80:83], v[162:165], v[194:197], v[80:83]
	v_mfma_f32_16x16x32_bf16 v[80:83], v[166:169], v[198:201], v[80:83]
	v_mfma_f32_16x16x32_bf16 v[72:75], v[174:177], v[198:201], v[72:75]
	v_mfma_f32_16x16x32_bf16 v[72:75], v[170:173], v[194:197], v[72:75]
	v_mfma_f32_16x16x32_bf16 v[64:67], v[170:173], v[202:205], v[64:67]
	v_mfma_f32_16x16x32_bf16 v[64:67], v[174:177], v[206:209], v[64:67]
	v_mfma_f32_16x16x32_bf16 v[68:71], v[166:169], v[206:209], v[68:71]
	v_mfma_f32_16x16x32_bf16 v[68:71], v[162:165], v[202:205], v[68:71]
	s_setprio 2
	s_barrier
	v_mfma_f32_16x16x32_bf16 v[76:79], v[146:149], v[202:205], v[76:79]
	v_mfma_f32_16x16x32_bf16 v[76:79], v[158:161], v[206:209], v[76:79]
	v_mfma_f32_16x16x32_bf16 v[84:87], v[132:135], v[206:209], v[84:87]
	v_mfma_f32_16x16x32_bf16 v[84:87], v[128:131], v[202:205], v[84:87]
	s_setprio 0
	s_add_i32 s36, s82, s63
	s_mov_b32 m0, s36
	ds_read_b128 v[178:181], v155 offset:16384
	ds_read_b128 v[182:185], v155 offset:17408
	ds_read_b128 v[186:189], v155 offset:18432
	ds_read_b128 v[190:193], v155 offset:19456
	ds_read_b128 v[194:197], v155 offset:20480
	ds_read_b128 v[198:201], v155 offset:21504
	ds_read_b128 v[202:205], v155 offset:22528
	ds_read_b128 v[206:209], v155 offset:23552
	global_load_lds_dwordx4 v138, vcc
	s_add_i32 m0, s36, 0x2000
	s_add_i32 s36, s83, s63
	s_add_u32 s98, vcc_lo, s0
	s_addc_u32 s99, vcc_hi, s1
	global_load_lds_dwordx4 v138, s[98:99]
	s_mov_b32 m0, s36
	s_nop 0
	s_add_u32 s98, vcc_lo, s6
	s_addc_u32 s99, vcc_hi, s7
	global_load_lds_dwordx4 v138, s[98:99]
	s_add_i32 m0, s36, 0x2000
	s_nop 0
	s_add_u32 s98, vcc_lo, s8
	s_addc_u32 s99, vcc_hi, s9
	global_load_lds_dwordx4 v138, s[98:99]
	s_mov_b32 m0, s33
	s_nop 0
	global_load_lds_dwordx4 v136, s[96:97]
	s_mov_b32 m0, s55
	s_nop 0
	s_add_u32 s98, s96, s0
	s_addc_u32 s99, s97, s1
	global_load_lds_dwordx4 v136, s[98:99]
	s_waitcnt vmcnt(8)
	s_waitcnt lgkmcnt(0)
	s_barrier
	s_setprio 1
	s_waitcnt lgkmcnt(0)
	v_mfma_f32_16x16x32_bf16 v[60:63], v[128:131], v[178:181], v[60:63]
	v_mfma_f32_16x16x32_bf16 v[60:63], v[132:135], v[182:185], v[60:63]
	v_mfma_f32_16x16x32_bf16 v[56:59], v[158:161], v[182:185], v[56:59]
	v_mfma_f32_16x16x32_bf16 v[56:59], v[146:149], v[178:181], v[56:59]
	v_mfma_f32_16x16x32_bf16 v[48:51], v[162:165], v[178:181], v[48:51]
	v_mfma_f32_16x16x32_bf16 v[48:51], v[166:169], v[182:185], v[48:51]
	v_mfma_f32_16x16x32_bf16 v[40:43], v[174:177], v[182:185], v[40:43]
	v_mfma_f32_16x16x32_bf16 v[40:43], v[170:173], v[178:181], v[40:43]
	v_mfma_f32_16x16x32_bf16 v[24:27], v[170:173], v[186:189], v[24:27]
	v_mfma_f32_16x16x32_bf16 v[24:27], v[174:177], v[190:193], v[24:27]
	v_mfma_f32_16x16x32_bf16 v[32:35], v[166:169], v[190:193], v[32:35]
	v_mfma_f32_16x16x32_bf16 v[32:35], v[162:165], v[186:189], v[32:35]
	v_mfma_f32_16x16x32_bf16 v[44:47], v[146:149], v[186:189], v[44:47]
	v_mfma_f32_16x16x32_bf16 v[44:47], v[158:161], v[190:193], v[44:47]
	v_mfma_f32_16x16x32_bf16 v[52:55], v[132:135], v[190:193], v[52:55]
	v_mfma_f32_16x16x32_bf16 v[52:55], v[128:131], v[186:189], v[52:55]
	s_setprio 0
	s_setprio 1
	v_mfma_f32_16x16x32_bf16 v[36:39], v[128:131], v[194:197], v[36:39]
	v_mfma_f32_16x16x32_bf16 v[36:39], v[132:135], v[198:201], v[36:39]
	v_mfma_f32_16x16x32_bf16 v[28:31], v[158:161], v[198:201], v[28:31]
	v_mfma_f32_16x16x32_bf16 v[28:31], v[146:149], v[194:197], v[28:31]
	v_mfma_f32_16x16x32_bf16 v[16:19], v[162:165], v[194:197], v[16:19]
	v_mfma_f32_16x16x32_bf16 v[16:19], v[166:169], v[198:201], v[16:19]
	v_mfma_f32_16x16x32_bf16 v[8:11], v[174:177], v[198:201], v[8:11]
	v_mfma_f32_16x16x32_bf16 v[8:11], v[170:173], v[194:197], v[8:11]
	v_mfma_f32_16x16x32_bf16 v[0:3], v[170:173], v[202:205], v[0:3]
	v_mfma_f32_16x16x32_bf16 v[0:3], v[174:177], v[206:209], v[0:3]
	v_mfma_f32_16x16x32_bf16 v[4:7], v[166:169], v[206:209], v[4:7]
	v_mfma_f32_16x16x32_bf16 v[4:7], v[162:165], v[202:205], v[4:7]
	s_setprio 2
	s_barrier
	v_mfma_f32_16x16x32_bf16 v[12:15], v[146:149], v[202:205], v[12:15]
	v_mfma_f32_16x16x32_bf16 v[12:15], v[158:161], v[206:209], v[12:15]
	v_mfma_f32_16x16x32_bf16 v[20:23], v[132:135], v[206:209], v[20:23]
	v_mfma_f32_16x16x32_bf16 v[20:23], v[128:131], v[202:205], v[20:23]
	s_setprio 0
	s_add_i32 s36, 0, 0x18000
	v_add_u32_e32 v157, s36, v152
	s_add_i32 s37, 0, 0x1c000
	ds_read_b128 v[128:131], v157
	ds_read_b128 v[132:135], v157 offset:1024
	ds_read_b128 v[146:149], v157 offset:2048
	ds_read_b128 v[158:161], v157 offset:3072
	v_add_u32_e32 v157, s37, v152
	ds_read_b128 v[162:165], v157
	ds_read_b128 v[166:169], v157 offset:1024
	ds_read_b128 v[170:173], v157 offset:2048
	ds_read_b128 v[174:177], v157 offset:3072
	s_mov_b32 m0, s57
	ds_read_b128 v[178:181], v155 offset:32768
	ds_read_b128 v[182:185], v155 offset:33792
	ds_read_b128 v[186:189], v155 offset:34816
	ds_read_b128 v[190:193], v155 offset:35840
	ds_read_b128 v[194:197], v155 offset:36864
	ds_read_b128 v[198:201], v155 offset:37888
	ds_read_b128 v[202:205], v155 offset:38912
	ds_read_b128 v[206:209], v155 offset:39936
	s_add_u32 s98, s96, s6
	s_addc_u32 s99, s97, s7
	global_load_lds_dwordx4 v136, s[98:99]
	s_mov_b32 m0, s59
	s_nop 0
	s_add_u32 s98, s96, s8
	s_addc_u32 s99, s97, s9
	global_load_lds_dwordx4 v136, s[98:99]
	s_waitcnt vmcnt(8)
	s_waitcnt lgkmcnt(0)
	s_barrier
	s_setprio 1
	s_waitcnt lgkmcnt(0)
	v_mfma_f32_16x16x32_bf16 v[124:127], v[128:131], v[178:181], v[124:127]
	v_mfma_f32_16x16x32_bf16 v[124:127], v[132:135], v[182:185], v[124:127]
	v_mfma_f32_16x16x32_bf16 v[120:123], v[158:161], v[182:185], v[120:123]
	v_mfma_f32_16x16x32_bf16 v[120:123], v[146:149], v[178:181], v[120:123]
	v_mfma_f32_16x16x32_bf16 v[116:119], v[162:165], v[178:181], v[116:119]
	v_mfma_f32_16x16x32_bf16 v[116:119], v[166:169], v[182:185], v[116:119]
	v_mfma_f32_16x16x32_bf16 v[104:107], v[174:177], v[182:185], v[104:107]
	v_mfma_f32_16x16x32_bf16 v[104:107], v[170:173], v[178:181], v[104:107]
	v_mfma_f32_16x16x32_bf16 v[88:91], v[170:173], v[186:189], v[88:91]
	v_mfma_f32_16x16x32_bf16 v[88:91], v[174:177], v[190:193], v[88:91]
	v_mfma_f32_16x16x32_bf16 v[96:99], v[166:169], v[190:193], v[96:99]
	v_mfma_f32_16x16x32_bf16 v[96:99], v[162:165], v[186:189], v[96:99]
	v_mfma_f32_16x16x32_bf16 v[108:111], v[146:149], v[186:189], v[108:111]
	v_mfma_f32_16x16x32_bf16 v[108:111], v[158:161], v[190:193], v[108:111]
	v_mfma_f32_16x16x32_bf16 v[112:115], v[132:135], v[190:193], v[112:115]
	v_mfma_f32_16x16x32_bf16 v[112:115], v[128:131], v[186:189], v[112:115]
	s_setprio 0
	s_setprio 1
	v_mfma_f32_16x16x32_bf16 v[100:103], v[128:131], v[194:197], v[100:103]
	v_mfma_f32_16x16x32_bf16 v[100:103], v[132:135], v[198:201], v[100:103]
	v_mfma_f32_16x16x32_bf16 v[92:95], v[158:161], v[198:201], v[92:95]
	v_mfma_f32_16x16x32_bf16 v[92:95], v[146:149], v[194:197], v[92:95]
	v_mfma_f32_16x16x32_bf16 v[80:83], v[162:165], v[194:197], v[80:83]
	v_mfma_f32_16x16x32_bf16 v[80:83], v[166:169], v[198:201], v[80:83]
	v_mfma_f32_16x16x32_bf16 v[72:75], v[174:177], v[198:201], v[72:75]
	v_mfma_f32_16x16x32_bf16 v[72:75], v[170:173], v[194:197], v[72:75]
	v_mfma_f32_16x16x32_bf16 v[64:67], v[170:173], v[202:205], v[64:67]
	v_mfma_f32_16x16x32_bf16 v[64:67], v[174:177], v[206:209], v[64:67]
	v_mfma_f32_16x16x32_bf16 v[68:71], v[166:169], v[206:209], v[68:71]
	v_mfma_f32_16x16x32_bf16 v[68:71], v[162:165], v[202:205], v[68:71]
	s_setprio 2
	s_barrier
	v_mfma_f32_16x16x32_bf16 v[76:79], v[146:149], v[202:205], v[76:79]
	v_mfma_f32_16x16x32_bf16 v[76:79], v[158:161], v[206:209], v[76:79]
	v_mfma_f32_16x16x32_bf16 v[84:87], v[132:135], v[206:209], v[84:87]
	v_mfma_f32_16x16x32_bf16 v[84:87], v[128:131], v[202:205], v[84:87]
	s_setprio 0
	s_add_i32 s36, s36, s63
	s_mov_b32 m0, s36
	ds_read_b128 v[178:181], v155 offset:49152
	ds_read_b128 v[182:185], v155 offset:50176
	ds_read_b128 v[186:189], v155 offset:51200
	ds_read_b128 v[190:193], v155 offset:52224
	ds_read_b128 v[194:197], v155 offset:53248
	ds_read_b128 v[198:201], v155 offset:54272
	ds_read_b128 v[202:205], v155 offset:55296
	ds_read_b128 v[206:209], v155 offset:56320
	s_add_u32 s98, vcc_lo, s24
	s_addc_u32 s99, vcc_hi, s25
	global_load_lds_dwordx4 v138, s[98:99]
	s_add_i32 m0, s36, 0x2000
	s_add_i32 s36, s37, s63
	s_add_u32 s98, vcc_lo, s34
	s_addc_u32 s99, vcc_hi, s35
	global_load_lds_dwordx4 v138, s[98:99]
	s_mov_b32 m0, s36
	s_add_u32 s98, vcc_lo, s12
	s_addc_u32 s99, vcc_hi, s13
	global_load_lds_dwordx4 v138, s[98:99]
	s_add_i32 m0, s36, 0x2000
	s_nop 0
	s_add_u32 s98, vcc_lo, s18
	s_addc_u32 s99, vcc_hi, s19
	global_load_lds_dwordx4 v138, s[98:99]
	s_mov_b32 m0, s68
	s_nop 0
	s_add_u32 s98, s96, s24
	s_addc_u32 s99, s97, s25
	global_load_lds_dwordx4 v136, s[98:99]
	s_mov_b32 m0, s69
	s_nop 0
	s_add_u32 s98, s96, s34
	s_addc_u32 s99, s97, s35
	global_load_lds_dwordx4 v136, s[98:99]
	s_waitcnt vmcnt(8)
	s_waitcnt lgkmcnt(0)
	s_barrier
	s_setprio 1
	s_waitcnt lgkmcnt(0)
	v_mfma_f32_16x16x32_bf16 v[60:63], v[128:131], v[178:181], v[60:63]
	v_mfma_f32_16x16x32_bf16 v[60:63], v[132:135], v[182:185], v[60:63]
	v_mfma_f32_16x16x32_bf16 v[56:59], v[158:161], v[182:185], v[56:59]
	v_mfma_f32_16x16x32_bf16 v[56:59], v[146:149], v[178:181], v[56:59]
	v_mfma_f32_16x16x32_bf16 v[48:51], v[162:165], v[178:181], v[48:51]
	v_mfma_f32_16x16x32_bf16 v[48:51], v[166:169], v[182:185], v[48:51]
	v_mfma_f32_16x16x32_bf16 v[40:43], v[174:177], v[182:185], v[40:43]
	v_mfma_f32_16x16x32_bf16 v[40:43], v[170:173], v[178:181], v[40:43]
	v_mfma_f32_16x16x32_bf16 v[24:27], v[170:173], v[186:189], v[24:27]
	v_mfma_f32_16x16x32_bf16 v[24:27], v[174:177], v[190:193], v[24:27]
	v_mfma_f32_16x16x32_bf16 v[32:35], v[166:169], v[190:193], v[32:35]
	v_mfma_f32_16x16x32_bf16 v[32:35], v[162:165], v[186:189], v[32:35]
	v_mfma_f32_16x16x32_bf16 v[44:47], v[146:149], v[186:189], v[44:47]
	v_mfma_f32_16x16x32_bf16 v[44:47], v[158:161], v[190:193], v[44:47]
	v_mfma_f32_16x16x32_bf16 v[52:55], v[132:135], v[190:193], v[52:55]
	v_mfma_f32_16x16x32_bf16 v[52:55], v[128:131], v[186:189], v[52:55]
	s_setprio 0
	s_setprio 1
	v_mfma_f32_16x16x32_bf16 v[36:39], v[128:131], v[194:197], v[36:39]
	v_mfma_f32_16x16x32_bf16 v[36:39], v[132:135], v[198:201], v[36:39]
	v_mfma_f32_16x16x32_bf16 v[28:31], v[158:161], v[198:201], v[28:31]
	v_mfma_f32_16x16x32_bf16 v[28:31], v[146:149], v[194:197], v[28:31]
	v_mfma_f32_16x16x32_bf16 v[16:19], v[162:165], v[194:197], v[16:19]
	v_mfma_f32_16x16x32_bf16 v[16:19], v[166:169], v[198:201], v[16:19]
	v_mfma_f32_16x16x32_bf16 v[8:11], v[174:177], v[198:201], v[8:11]
	v_mfma_f32_16x16x32_bf16 v[8:11], v[170:173], v[194:197], v[8:11]
	v_mfma_f32_16x16x32_bf16 v[0:3], v[170:173], v[202:205], v[0:3]
	v_mfma_f32_16x16x32_bf16 v[0:3], v[174:177], v[206:209], v[0:3]
	v_mfma_f32_16x16x32_bf16 v[4:7], v[166:169], v[206:209], v[4:7]
	v_mfma_f32_16x16x32_bf16 v[4:7], v[162:165], v[202:205], v[4:7]
	s_setprio 2
	s_barrier
	v_mfma_f32_16x16x32_bf16 v[12:15], v[146:149], v[202:205], v[12:15]
	v_mfma_f32_16x16x32_bf16 v[12:15], v[158:161], v[206:209], v[12:15]
	v_mfma_f32_16x16x32_bf16 v[20:23], v[132:135], v[206:209], v[20:23]
	v_mfma_f32_16x16x32_bf16 v[20:23], v[128:131], v[202:205], v[20:23]
	s_setprio 0
	s_add_i32 s81, s81, 2
	s_add_u32 s22, s22, 0x100
	s_addc_u32 s80, s80, 0
	s_add_u32 s78, s78, 0x100
	s_addc_u32 s79, s79, 0
	s_cmp_gt_u32 s81, 61
	s_cbranch_scc0 .LBB0_298
	s_and_b64 vcc, exec, s[26:27]
	s_cbranch_vccz .LBB0_301
	s_barrier

.LBB0_627:
	ds_read_b128 v[128:131], v151
	ds_read_b128 v[142:145], v151 offset:1024
	ds_read_b128 v[146:149], v151 offset:2048
	ds_read_b128 v[154:157], v151 offset:3072
	ds_read_b128 v[158:161], v152
	ds_read_b128 v[162:165], v152 offset:1024
	ds_read_b128 v[166:169], v152 offset:2048
	ds_read_b128 v[170:173], v152 offset:3072
	s_add_u32 s50, s60, 0xfff00080
	s_addc_u32 s51, s61, -1
	s_cmp_eq_u32 s62, 60
	s_cselect_b32 s77, s5, s51
	s_cselect_b32 s76, s49, s50
	s_cselect_b32 s79, s47, s75
	s_cselect_b32 s78, s59, s74
	s_add_i32 m0, s20, 0xc000
	ds_read_b128 v[174:177], v153
	ds_read_b128 v[178:181], v153 offset:1024
	ds_read_b128 v[182:185], v153 offset:2048
	ds_read_b128 v[186:189], v153 offset:3072
	ds_read_b128 v[190:193], v153 offset:4096
	ds_read_b128 v[194:197], v153 offset:5120
	ds_read_b128 v[198:201], v153 offset:6144
	ds_read_b128 v[202:205], v153 offset:7168
	global_load_lds_dwordx4 v136, s[60:61]
	s_add_i32 m0, s20, 0xe000
	s_nop 0
	s_add_u32 s98, s60, s6
	s_addc_u32 s99, s61, s7
	global_load_lds_dwordx4 v136, s[98:99]
	s_waitcnt vmcnt(8)
	s_waitcnt lgkmcnt(0)
	s_barrier
	s_setprio 1
	s_waitcnt lgkmcnt(0)
	v_mfma_f32_16x16x32_bf16 v[124:127], v[128:131], v[174:177], v[124:127]
	v_mfma_f32_16x16x32_bf16 v[124:127], v[142:145], v[178:181], v[124:127]
	v_mfma_f32_16x16x32_bf16 v[120:123], v[154:157], v[178:181], v[120:123]
	v_mfma_f32_16x16x32_bf16 v[120:123], v[146:149], v[174:177], v[120:123]
	v_mfma_f32_16x16x32_bf16 v[92:95], v[158:161], v[174:177], v[92:95]
	v_mfma_f32_16x16x32_bf16 v[92:95], v[162:165], v[178:181], v[92:95]
	v_mfma_f32_16x16x32_bf16 v[88:91], v[170:173], v[178:181], v[88:91]
	v_mfma_f32_16x16x32_bf16 v[88:91], v[166:169], v[174:177], v[88:91]
	v_mfma_f32_16x16x32_bf16 v[80:83], v[166:169], v[182:185], v[80:83]
	v_mfma_f32_16x16x32_bf16 v[80:83], v[170:173], v[186:189], v[80:83]
	v_mfma_f32_16x16x32_bf16 v[84:87], v[162:165], v[186:189], v[84:87]
	v_mfma_f32_16x16x32_bf16 v[84:87], v[158:161], v[182:185], v[84:87]
	v_mfma_f32_16x16x32_bf16 v[112:115], v[146:149], v[182:185], v[112:115]
	v_mfma_f32_16x16x32_bf16 v[112:115], v[154:157], v[186:189], v[112:115]
	v_mfma_f32_16x16x32_bf16 v[116:119], v[142:145], v[186:189], v[116:119]
	v_mfma_f32_16x16x32_bf16 v[116:119], v[128:131], v[182:185], v[116:119]
	s_setprio 0
	s_setprio 1
	v_mfma_f32_16x16x32_bf16 v[108:111], v[128:131], v[190:193], v[108:111]
	v_mfma_f32_16x16x32_bf16 v[108:111], v[142:145], v[194:197], v[108:111]
	v_mfma_f32_16x16x32_bf16 v[104:107], v[154:157], v[194:197], v[104:107]
	v_mfma_f32_16x16x32_bf16 v[104:107], v[146:149], v[190:193], v[104:107]
	v_mfma_f32_16x16x32_bf16 v[76:79], v[158:161], v[190:193], v[76:79]
	v_mfma_f32_16x16x32_bf16 v[76:79], v[162:165], v[194:197], v[76:79]
	v_mfma_f32_16x16x32_bf16 v[72:75], v[170:173], v[194:197], v[72:75]
	v_mfma_f32_16x16x32_bf16 v[72:75], v[166:169], v[190:193], v[72:75]
	v_mfma_f32_16x16x32_bf16 v[64:67], v[166:169], v[198:201], v[64:67]
	v_mfma_f32_16x16x32_bf16 v[64:67], v[170:173], v[202:205], v[64:67]
	v_mfma_f32_16x16x32_bf16 v[68:71], v[162:165], v[202:205], v[68:71]
	v_mfma_f32_16x16x32_bf16 v[68:71], v[158:161], v[198:201], v[68:71]
	s_setprio 2
	s_barrier
	v_mfma_f32_16x16x32_bf16 v[96:99], v[146:149], v[198:201], v[96:99]
	v_mfma_f32_16x16x32_bf16 v[96:99], v[154:157], v[202:205], v[96:99]
	v_mfma_f32_16x16x32_bf16 v[100:103], v[142:145], v[202:205], v[100:103]
	v_mfma_f32_16x16x32_bf16 v[100:103], v[128:131], v[198:201], v[100:103]
	s_setprio 0
	s_add_i32 s50, s72, s14
	s_mov_b32 m0, s50
	ds_read_b128 v[174:177], v153 offset:16384
	ds_read_b128 v[178:181], v153 offset:17408
	ds_read_b128 v[182:185], v153 offset:18432
	ds_read_b128 v[186:189], v153 offset:19456
	ds_read_b128 v[190:193], v153 offset:20480
	ds_read_b128 v[194:197], v153 offset:21504
	ds_read_b128 v[198:201], v153 offset:22528
	ds_read_b128 v[202:205], v153 offset:23552
	global_load_lds_dwordx4 v134, s[78:79]
	s_add_i32 m0, s50, 0x2000
	s_add_i32 s50, s73, s14
	s_add_u32 s98, s78, s6
	s_addc_u32 s99, s79, s7
	global_load_lds_dwordx4 v134, s[98:99]
	s_mov_b32 m0, s50
	s_nop 0
	s_add_u32 s98, s78, s8
	s_addc_u32 s99, s79, s9
	global_load_lds_dwordx4 v134, s[98:99]
	s_add_i32 m0, s50, 0x2000
	s_nop 0
	s_add_u32 s98, s78, s10
	s_addc_u32 s99, s79, s11
	global_load_lds_dwordx4 v134, s[98:99]
	s_mov_b32 m0, s20
	s_nop 0
	global_load_lds_dwordx4 v132, s[76:77]
	s_mov_b32 m0, s21
	s_nop 0
	s_add_u32 s98, s76, s6
	s_addc_u32 s99, s77, s7
	global_load_lds_dwordx4 v132, s[98:99]
	s_waitcnt vmcnt(8)
	s_waitcnt lgkmcnt(0)
	s_barrier
	s_setprio 1
	s_waitcnt lgkmcnt(0)
	v_mfma_f32_16x16x32_bf16 v[60:63], v[128:131], v[174:177], v[60:63]
	v_mfma_f32_16x16x32_bf16 v[60:63], v[142:145], v[178:181], v[60:63]
	v_mfma_f32_16x16x32_bf16 v[56:59], v[154:157], v[178:181], v[56:59]
	v_mfma_f32_16x16x32_bf16 v[56:59], v[146:149], v[174:177], v[56:59]
	v_mfma_f32_16x16x32_bf16 v[28:31], v[158:161], v[174:177], v[28:31]
	v_mfma_f32_16x16x32_bf16 v[28:31], v[162:165], v[178:181], v[28:31]
	v_mfma_f32_16x16x32_bf16 v[24:27], v[170:173], v[178:181], v[24:27]
	v_mfma_f32_16x16x32_bf16 v[24:27], v[166:169], v[174:177], v[24:27]
	v_mfma_f32_16x16x32_bf16 v[16:19], v[166:169], v[182:185], v[16:19]
	v_mfma_f32_16x16x32_bf16 v[16:19], v[170:173], v[186:189], v[16:19]
	v_mfma_f32_16x16x32_bf16 v[20:23], v[162:165], v[186:189], v[20:23]
	v_mfma_f32_16x16x32_bf16 v[20:23], v[158:161], v[182:185], v[20:23]
	v_mfma_f32_16x16x32_bf16 v[48:51], v[146:149], v[182:185], v[48:51]
	v_mfma_f32_16x16x32_bf16 v[48:51], v[154:157], v[186:189], v[48:51]
	v_mfma_f32_16x16x32_bf16 v[52:55], v[142:145], v[186:189], v[52:55]
	v_mfma_f32_16x16x32_bf16 v[52:55], v[128:131], v[182:185], v[52:55]
	s_setprio 0
	s_setprio 1
	v_mfma_f32_16x16x32_bf16 v[44:47], v[128:131], v[190:193], v[44:47]
	v_mfma_f32_16x16x32_bf16 v[44:47], v[142:145], v[194:197], v[44:47]
	v_mfma_f32_16x16x32_bf16 v[40:43], v[154:157], v[194:197], v[40:43]
	v_mfma_f32_16x16x32_bf16 v[40:43], v[146:149], v[190:193], v[40:43]
	v_mfma_f32_16x16x32_bf16 v[12:15], v[158:161], v[190:193], v[12:15]
	v_mfma_f32_16x16x32_bf16 v[12:15], v[162:165], v[194:197], v[12:15]
	v_mfma_f32_16x16x32_bf16 v[8:11], v[170:173], v[194:197], v[8:11]
	v_mfma_f32_16x16x32_bf16 v[8:11], v[166:169], v[190:193], v[8:11]
	v_mfma_f32_16x16x32_bf16 v[0:3], v[166:169], v[198:201], v[0:3]
	v_mfma_f32_16x16x32_bf16 v[0:3], v[170:173], v[202:205], v[0:3]
	v_mfma_f32_16x16x32_bf16 v[4:7], v[162:165], v[202:205], v[4:7]
	v_mfma_f32_16x16x32_bf16 v[4:7], v[158:161], v[198:201], v[4:7]
	s_setprio 2
	s_barrier
	v_mfma_f32_16x16x32_bf16 v[32:35], v[146:149], v[198:201], v[32:35]
	v_mfma_f32_16x16x32_bf16 v[32:35], v[154:157], v[202:205], v[32:35]
	v_mfma_f32_16x16x32_bf16 v[36:39], v[142:145], v[202:205], v[36:39]
	v_mfma_f32_16x16x32_bf16 v[36:39], v[128:131], v[198:201], v[36:39]
	s_setprio 0
	s_add_i32 s50, 0, 0x18000
	s_add_i32 s51, 0, 0x1c000
	v_add_u32_e32 v154, s50, v150
	v_add_u32_e32 v170, s51, v150
	ds_read_b128 v[128:131], v154
	ds_read_b128 v[142:145], v154 offset:1024
	ds_read_b128 v[146:149], v154 offset:2048
	ds_read_b128 v[154:157], v154 offset:3072
	ds_read_b128 v[158:161], v170
	ds_read_b128 v[162:165], v170 offset:1024
	ds_read_b128 v[166:169], v170 offset:2048
	ds_read_b128 v[170:173], v170 offset:3072
	s_mov_b32 m0, s33
	ds_read_b128 v[174:177], v153 offset:32768
	ds_read_b128 v[178:181], v153 offset:33792
	ds_read_b128 v[182:185], v153 offset:34816
	ds_read_b128 v[186:189], v153 offset:35840
	ds_read_b128 v[190:193], v153 offset:36864
	ds_read_b128 v[194:197], v153 offset:37888
	ds_read_b128 v[198:201], v153 offset:38912
	ds_read_b128 v[202:205], v153 offset:39936
	s_add_u32 s98, s76, s8
	s_addc_u32 s99, s77, s9
	global_load_lds_dwordx4 v132, s[98:99]
	s_mov_b32 m0, s64
	s_nop 0
	s_add_u32 s98, s76, s10
	s_addc_u32 s99, s77, s11
	global_load_lds_dwordx4 v132, s[98:99]
	s_waitcnt vmcnt(8)
	s_waitcnt lgkmcnt(0)
	s_barrier
	s_setprio 1
	s_waitcnt lgkmcnt(0)
	v_mfma_f32_16x16x32_bf16 v[124:127], v[128:131], v[174:177], v[124:127]
	v_mfma_f32_16x16x32_bf16 v[124:127], v[142:145], v[178:181], v[124:127]
	v_mfma_f32_16x16x32_bf16 v[120:123], v[154:157], v[178:181], v[120:123]
	v_mfma_f32_16x16x32_bf16 v[120:123], v[146:149], v[174:177], v[120:123]
	v_mfma_f32_16x16x32_bf16 v[92:95], v[158:161], v[174:177], v[92:95]
	v_mfma_f32_16x16x32_bf16 v[92:95], v[162:165], v[178:181], v[92:95]
	v_mfma_f32_16x16x32_bf16 v[88:91], v[170:173], v[178:181], v[88:91]
	v_mfma_f32_16x16x32_bf16 v[88:91], v[166:169], v[174:177], v[88:91]
	v_mfma_f32_16x16x32_bf16 v[80:83], v[166:169], v[182:185], v[80:83]
	v_mfma_f32_16x16x32_bf16 v[80:83], v[170:173], v[186:189], v[80:83]
	v_mfma_f32_16x16x32_bf16 v[84:87], v[162:165], v[186:189], v[84:87]
	v_mfma_f32_16x16x32_bf16 v[84:87], v[158:161], v[182:185], v[84:87]
	v_mfma_f32_16x16x32_bf16 v[112:115], v[146:149], v[182:185], v[112:115]
	v_mfma_f32_16x16x32_bf16 v[112:115], v[154:157], v[186:189], v[112:115]
	v_mfma_f32_16x16x32_bf16 v[116:119], v[142:145], v[186:189], v[116:119]
	v_mfma_f32_16x16x32_bf16 v[116:119], v[128:131], v[182:185], v[116:119]
	s_setprio 0
	s_setprio 1
	v_mfma_f32_16x16x32_bf16 v[108:111], v[128:131], v[190:193], v[108:111]
	v_mfma_f32_16x16x32_bf16 v[108:111], v[142:145], v[194:197], v[108:111]
	v_mfma_f32_16x16x32_bf16 v[104:107], v[154:157], v[194:197], v[104:107]
	v_mfma_f32_16x16x32_bf16 v[104:107], v[146:149], v[190:193], v[104:107]
	v_mfma_f32_16x16x32_bf16 v[76:79], v[158:161], v[190:193], v[76:79]
	v_mfma_f32_16x16x32_bf16 v[76:79], v[162:165], v[194:197], v[76:79]
	v_mfma_f32_16x16x32_bf16 v[72:75], v[170:173], v[194:197], v[72:75]
	v_mfma_f32_16x16x32_bf16 v[72:75], v[166:169], v[190:193], v[72:75]
	v_mfma_f32_16x16x32_bf16 v[64:67], v[166:169], v[198:201], v[64:67]
	v_mfma_f32_16x16x32_bf16 v[64:67], v[170:173], v[202:205], v[64:67]
	v_mfma_f32_16x16x32_bf16 v[68:71], v[162:165], v[202:205], v[68:71]
	v_mfma_f32_16x16x32_bf16 v[68:71], v[158:161], v[198:201], v[68:71]
	s_setprio 2
	s_barrier
	v_mfma_f32_16x16x32_bf16 v[96:99], v[146:149], v[198:201], v[96:99]
	v_mfma_f32_16x16x32_bf16 v[96:99], v[154:157], v[202:205], v[96:99]
	v_mfma_f32_16x16x32_bf16 v[100:103], v[142:145], v[202:205], v[100:103]
	v_mfma_f32_16x16x32_bf16 v[100:103], v[128:131], v[198:201], v[100:103]
	s_setprio 0
	s_add_i32 s50, s50, s14
	s_mov_b32 m0, s50
	ds_read_b128 v[174:177], v153 offset:49152
	ds_read_b128 v[178:181], v153 offset:50176
	ds_read_b128 v[182:185], v153 offset:51200
	ds_read_b128 v[186:189], v153 offset:52224
	ds_read_b128 v[190:193], v153 offset:53248
	ds_read_b128 v[194:197], v153 offset:54272
	ds_read_b128 v[198:201], v153 offset:55296
	ds_read_b128 v[202:205], v153 offset:56320
	s_add_u32 s98, s78, s24
	s_addc_u32 s99, s79, s25
	global_load_lds_dwordx4 v134, s[98:99]
	s_add_i32 m0, s50, 0x2000
	s_add_i32 s50, s51, s14
	s_add_u32 s98, s78, s34
	s_addc_u32 s99, s79, s35
	global_load_lds_dwordx4 v134, s[98:99]
	s_mov_b32 m0, s50
	s_add_u32 s98, s78, s36
	s_addc_u32 s99, s79, s37
	global_load_lds_dwordx4 v134, s[98:99]
	s_add_i32 m0, s50, 0x2000
	s_nop 0
	s_add_u32 s98, s78, s38
	s_addc_u32 s99, s79, s39
	global_load_lds_dwordx4 v134, s[98:99]
	s_mov_b32 m0, s66
	s_nop 0
	s_add_u32 s98, s76, s24
	s_addc_u32 s99, s77, s25
	global_load_lds_dwordx4 v132, s[98:99]
	s_mov_b32 m0, s67
	s_nop 0
	s_add_u32 s98, s76, s34
	s_addc_u32 s99, s77, s35
	global_load_lds_dwordx4 v132, s[98:99]
	s_waitcnt vmcnt(8)
	s_waitcnt lgkmcnt(0)
	s_barrier
	s_setprio 1
	s_waitcnt lgkmcnt(0)
	v_mfma_f32_16x16x32_bf16 v[60:63], v[128:131], v[174:177], v[60:63]
	v_mfma_f32_16x16x32_bf16 v[60:63], v[142:145], v[178:181], v[60:63]
	v_mfma_f32_16x16x32_bf16 v[56:59], v[154:157], v[178:181], v[56:59]
	v_mfma_f32_16x16x32_bf16 v[56:59], v[146:149], v[174:177], v[56:59]
	v_mfma_f32_16x16x32_bf16 v[28:31], v[158:161], v[174:177], v[28:31]
	v_mfma_f32_16x16x32_bf16 v[28:31], v[162:165], v[178:181], v[28:31]
	v_mfma_f32_16x16x32_bf16 v[24:27], v[170:173], v[178:181], v[24:27]
	v_mfma_f32_16x16x32_bf16 v[24:27], v[166:169], v[174:177], v[24:27]
	v_mfma_f32_16x16x32_bf16 v[16:19], v[166:169], v[182:185], v[16:19]
	v_mfma_f32_16x16x32_bf16 v[16:19], v[170:173], v[186:189], v[16:19]
	v_mfma_f32_16x16x32_bf16 v[20:23], v[162:165], v[186:189], v[20:23]
	v_mfma_f32_16x16x32_bf16 v[20:23], v[158:161], v[182:185], v[20:23]
	v_mfma_f32_16x16x32_bf16 v[48:51], v[146:149], v[182:185], v[48:51]
	v_mfma_f32_16x16x32_bf16 v[48:51], v[154:157], v[186:189], v[48:51]
	v_mfma_f32_16x16x32_bf16 v[52:55], v[142:145], v[186:189], v[52:55]
	v_mfma_f32_16x16x32_bf16 v[52:55], v[128:131], v[182:185], v[52:55]
	s_setprio 0
	s_setprio 1
	v_mfma_f32_16x16x32_bf16 v[44:47], v[128:131], v[190:193], v[44:47]
	v_mfma_f32_16x16x32_bf16 v[44:47], v[142:145], v[194:197], v[44:47]
	v_mfma_f32_16x16x32_bf16 v[40:43], v[154:157], v[194:197], v[40:43]
	v_mfma_f32_16x16x32_bf16 v[40:43], v[146:149], v[190:193], v[40:43]
	v_mfma_f32_16x16x32_bf16 v[12:15], v[158:161], v[190:193], v[12:15]
	v_mfma_f32_16x16x32_bf16 v[12:15], v[162:165], v[194:197], v[12:15]
	v_mfma_f32_16x16x32_bf16 v[8:11], v[170:173], v[194:197], v[8:11]
	v_mfma_f32_16x16x32_bf16 v[8:11], v[166:169], v[190:193], v[8:11]
	v_mfma_f32_16x16x32_bf16 v[0:3], v[166:169], v[198:201], v[0:3]
	v_mfma_f32_16x16x32_bf16 v[0:3], v[170:173], v[202:205], v[0:3]
	v_mfma_f32_16x16x32_bf16 v[4:7], v[162:165], v[202:205], v[4:7]
	v_mfma_f32_16x16x32_bf16 v[4:7], v[158:161], v[198:201], v[4:7]
	s_setprio 2
	s_barrier
	v_mfma_f32_16x16x32_bf16 v[32:35], v[146:149], v[198:201], v[32:35]
	v_mfma_f32_16x16x32_bf16 v[32:35], v[154:157], v[202:205], v[32:35]
	v_mfma_f32_16x16x32_bf16 v[36:39], v[142:145], v[202:205], v[36:39]
	v_mfma_f32_16x16x32_bf16 v[36:39], v[128:131], v[198:201], v[36:39]
	s_setprio 0
	s_add_i32 s62, s62, 2
	s_add_u32 s74, s74, 0x100
	s_addc_u32 s75, s75, 0
	s_add_u32 s60, s60, 0x100
	s_addc_u32 s61, s61, 0
	s_cmp_gt_u32 s62, 61
	s_cbranch_scc0 .LBB0_627
	s_and_b64 vcc, exec, s[40:41]
	s_cbranch_vccz .LBB0_630
	s_barrier

.Lcm4_skip:
.LBB0_800:
	ds_read_b128 v[128:131], v187
	ds_read_b128 v[132:135], v187 offset:1024
	ds_read_b128 v[136:139], v187 offset:2048
	ds_read_b128 v[140:143], v187 offset:3072
	ds_read_b128 v[144:147], v188
	ds_read_b128 v[148:151], v188 offset:1024
	ds_read_b128 v[152:155], v188 offset:2048
	ds_read_b128 v[156:159], v188 offset:3072
	s_add_u32 s9, s6, 0xfff80080
	s_addc_u32 s50, s7, -1
	s_cmp_eq_u32 s8, 28
	s_cselect_b32 vcc_hi, s5, s50
	s_cselect_b32 vcc_lo, s10, s9
	s_cselect_b32 s51, s11, s78
	s_cselect_b32 s50, s73, s75
	s_add_i32 m0, s65, 0xc000
	ds_read_b128 v[160:163], v189
	ds_read_b128 v[164:167], v189 offset:1024
	ds_read_b128 v[168:171], v189 offset:2048
	ds_read_b128 v[192:195], v189 offset:3072
	ds_read_b128 v[196:199], v189 offset:4096
	ds_read_b128 v[200:203], v189 offset:5120
	ds_read_b128 v[204:207], v189 offset:6144
	ds_read_b128 v[208:211], v189 offset:7168
	global_load_lds_dwordx4 v178, s[6:7]
	s_add_i32 m0, s65, 0xe000
	s_nop 0
	s_add_u32 s98, s6, s36
	s_addc_u32 s99, s7, s37
	global_load_lds_dwordx4 v178, s[98:99]
	s_waitcnt vmcnt(8)
	s_waitcnt lgkmcnt(0)
	s_barrier
	s_setprio 1
	s_waitcnt lgkmcnt(0)
	v_mfma_i32_16x16x64_i8 v[84:87], v[128:131], v[160:163], v[84:87]
	v_mfma_i32_16x16x64_i8 v[84:87], v[132:135], v[164:167], v[84:87]
	v_mfma_i32_16x16x64_i8 v[16:19], v[140:143], v[164:167], v[16:19]
	v_mfma_i32_16x16x64_i8 v[16:19], v[136:139], v[160:163], v[16:19]
	v_mfma_i32_16x16x64_i8 v[124:127], v[144:147], v[160:163], v[124:127]
	v_mfma_i32_16x16x64_i8 v[124:127], v[148:151], v[164:167], v[124:127]
	v_mfma_i32_16x16x64_i8 v[68:71], v[156:159], v[164:167], v[68:71]
	v_mfma_i32_16x16x64_i8 v[68:71], v[152:155], v[160:163], v[68:71]
	v_mfma_i32_16x16x64_i8 v[72:75], v[152:155], v[168:171], v[72:75]
	v_mfma_i32_16x16x64_i8 v[72:75], v[156:159], v[192:195], v[72:75]
	v_mfma_i32_16x16x64_i8 v[120:123], v[148:151], v[192:195], v[120:123]
	v_mfma_i32_16x16x64_i8 v[120:123], v[144:147], v[168:171], v[120:123]
	v_mfma_i32_16x16x64_i8 v[20:23], v[136:139], v[168:171], v[20:23]
	v_mfma_i32_16x16x64_i8 v[20:23], v[140:143], v[192:195], v[20:23]
	v_mfma_i32_16x16x64_i8 v[88:91], v[132:135], v[192:195], v[88:91]
	v_mfma_i32_16x16x64_i8 v[88:91], v[128:131], v[168:171], v[88:91]
	s_setprio 0
	s_setprio 1
	v_mfma_i32_16x16x64_i8 v[92:95], v[128:131], v[196:199], v[92:95]
	v_mfma_i32_16x16x64_i8 v[92:95], v[132:135], v[200:203], v[92:95]
	v_mfma_i32_16x16x64_i8 v[24:27], v[140:143], v[200:203], v[24:27]
	v_mfma_i32_16x16x64_i8 v[24:27], v[136:139], v[196:199], v[24:27]
	v_mfma_i32_16x16x64_i8 v[116:119], v[144:147], v[196:199], v[116:119]
	v_mfma_i32_16x16x64_i8 v[116:119], v[148:151], v[200:203], v[116:119]
	v_mfma_i32_16x16x64_i8 v[80:83], v[156:159], v[200:203], v[80:83]
	v_mfma_i32_16x16x64_i8 v[80:83], v[152:155], v[196:199], v[80:83]
	v_mfma_i32_16x16x64_i8 v[60:63], v[152:155], v[204:207], v[60:63]
	v_mfma_i32_16x16x64_i8 v[60:63], v[156:159], v[208:211], v[60:63]
	v_mfma_i32_16x16x64_i8 v[112:115], v[148:151], v[208:211], v[112:115]
	v_mfma_i32_16x16x64_i8 v[112:115], v[144:147], v[204:207], v[112:115]
	s_setprio 2
	s_barrier
	v_mfma_i32_16x16x64_i8 v[28:31], v[136:139], v[204:207], v[28:31]
	v_mfma_i32_16x16x64_i8 v[28:31], v[140:143], v[208:211], v[28:31]
	v_mfma_i32_16x16x64_i8 v[96:99], v[132:135], v[208:211], v[96:99]
	v_mfma_i32_16x16x64_i8 v[96:99], v[128:131], v[204:207], v[96:99]
	s_setprio 0
	s_add_i32 s9, s80, s33
	s_mov_b64 s[100:101], s[50:51]
	s_mov_b32 m0, s9
	ds_read_b128 v[160:163], v189 offset:16384
	ds_read_b128 v[164:167], v189 offset:17408
	ds_read_b128 v[168:171], v189 offset:18432
	ds_read_b128 v[192:195], v189 offset:19456
	ds_read_b128 v[196:199], v189 offset:20480
	ds_read_b128 v[200:203], v189 offset:21504
	ds_read_b128 v[204:207], v189 offset:22528
	ds_read_b128 v[208:211], v189 offset:23552
	global_load_lds_dwordx4 v174, s[50:51]
	s_add_i32 m0, s9, 0x2000
	s_add_i32 s9, s81, s33
	s_add_u32 s98, s50, s36
	s_addc_u32 s99, s51, s37
	global_load_lds_dwordx4 v174, s[98:99]
	s_mov_b32 m0, s9
	s_nop 0
	s_add_u32 s98, s50, s38
	s_addc_u32 s99, s51, s39
	global_load_lds_dwordx4 v174, s[98:99]
	s_add_i32 m0, s9, 0x2000
	s_nop 0
	s_add_u32 s98, s50, s40
	s_addc_u32 s99, s51, s41
	global_load_lds_dwordx4 v174, s[98:99]
	s_mov_b32 m0, s65
	s_nop 0
	global_load_lds_dwordx4 v172, vcc
	s_mov_b32 m0, s67
	s_nop 0
	s_add_u32 s98, vcc_lo, s36
	s_addc_u32 s99, vcc_hi, s37
	global_load_lds_dwordx4 v172, s[98:99]
	s_waitcnt vmcnt(8)
	s_waitcnt lgkmcnt(0)
	s_barrier
	s_setprio 1
	s_waitcnt lgkmcnt(0)
	v_mfma_i32_16x16x64_i8 v[48:51], v[128:131], v[160:163], v[48:51]
	v_mfma_i32_16x16x64_i8 v[48:51], v[132:135], v[164:167], v[48:51]
	v_mfma_i32_16x16x64_i8 v[0:3], v[140:143], v[164:167], v[0:3]
	v_mfma_i32_16x16x64_i8 v[0:3], v[136:139], v[160:163], v[0:3]
	v_mfma_i32_16x16x64_i8 v[108:111], v[144:147], v[160:163], v[108:111]
	v_mfma_i32_16x16x64_i8 v[108:111], v[148:151], v[164:167], v[108:111]
	v_mfma_i32_16x16x64_i8 v[44:47], v[156:159], v[164:167], v[44:47]
	v_mfma_i32_16x16x64_i8 v[44:47], v[152:155], v[160:163], v[44:47]
	v_mfma_i32_16x16x64_i8 v[40:43], v[152:155], v[168:171], v[40:43]
	v_mfma_i32_16x16x64_i8 v[40:43], v[156:159], v[192:195], v[40:43]
	v_mfma_i32_16x16x64_i8 v[104:107], v[148:151], v[192:195], v[104:107]
	v_mfma_i32_16x16x64_i8 v[104:107], v[144:147], v[168:171], v[104:107]
	v_mfma_i32_16x16x64_i8 v[4:7], v[136:139], v[168:171], v[4:7]
	v_mfma_i32_16x16x64_i8 v[4:7], v[140:143], v[192:195], v[4:7]
	v_mfma_i32_16x16x64_i8 v[52:55], v[132:135], v[192:195], v[52:55]
	v_mfma_i32_16x16x64_i8 v[52:55], v[128:131], v[168:171], v[52:55]
	s_setprio 0
	s_setprio 1
	v_mfma_i32_16x16x64_i8 v[56:59], v[128:131], v[196:199], v[56:59]
	v_mfma_i32_16x16x64_i8 v[56:59], v[132:135], v[200:203], v[56:59]
	v_mfma_i32_16x16x64_i8 v[8:11], v[140:143], v[200:203], v[8:11]
	v_mfma_i32_16x16x64_i8 v[8:11], v[136:139], v[196:199], v[8:11]
	v_mfma_i32_16x16x64_i8 v[100:103], v[144:147], v[196:199], v[100:103]
	v_mfma_i32_16x16x64_i8 v[100:103], v[148:151], v[200:203], v[100:103]
	v_mfma_i32_16x16x64_i8 v[32:35], v[156:159], v[200:203], v[32:35]
	v_mfma_i32_16x16x64_i8 v[32:35], v[152:155], v[196:199], v[32:35]
	v_mfma_i32_16x16x64_i8 v[36:39], v[152:155], v[204:207], v[36:39]
	v_mfma_i32_16x16x64_i8 v[36:39], v[156:159], v[208:211], v[36:39]
	v_mfma_i32_16x16x64_i8 v[76:79], v[148:151], v[208:211], v[76:79]
	v_mfma_i32_16x16x64_i8 v[76:79], v[144:147], v[204:207], v[76:79]
	s_setprio 2
	s_barrier
	v_mfma_i32_16x16x64_i8 v[12:15], v[136:139], v[204:207], v[12:15]
	v_mfma_i32_16x16x64_i8 v[12:15], v[140:143], v[208:211], v[12:15]
	v_mfma_i32_16x16x64_i8 v[64:67], v[132:135], v[208:211], v[64:67]
	v_mfma_i32_16x16x64_i8 v[64:67], v[128:131], v[204:207], v[64:67]
	s_setprio 0
	s_add_i32 s9, 0, 0x18000
	s_add_i32 s50, 0, 0x1c000
	v_add_u32_e32 v140, s9, v186
	v_add_u32_e32 v156, s50, v186
	ds_read_b128 v[128:131], v140
	ds_read_b128 v[132:135], v140 offset:1024
	ds_read_b128 v[136:139], v140 offset:2048
	ds_read_b128 v[140:143], v140 offset:3072
	ds_read_b128 v[144:147], v156
	ds_read_b128 v[148:151], v156 offset:1024
	ds_read_b128 v[152:155], v156 offset:2048
	ds_read_b128 v[156:159], v156 offset:3072
	s_mov_b32 m0, s71
	ds_read_b128 v[160:163], v189 offset:32768
	ds_read_b128 v[164:167], v189 offset:33792
	ds_read_b128 v[168:171], v189 offset:34816
	ds_read_b128 v[192:195], v189 offset:35840
	ds_read_b128 v[196:199], v189 offset:36864
	ds_read_b128 v[200:203], v189 offset:37888
	ds_read_b128 v[204:207], v189 offset:38912
	ds_read_b128 v[208:211], v189 offset:39936
	s_add_u32 s98, vcc_lo, s38
	s_addc_u32 s99, vcc_hi, s39
	global_load_lds_dwordx4 v172, s[98:99]
	s_mov_b32 m0, s82
	s_nop 0
	s_add_u32 s98, vcc_lo, s40
	s_addc_u32 s99, vcc_hi, s41
	global_load_lds_dwordx4 v172, s[98:99]
	s_waitcnt vmcnt(8)
	s_waitcnt lgkmcnt(0)
	s_barrier
	s_setprio 1
	s_waitcnt lgkmcnt(0)
	v_mfma_i32_16x16x64_i8 v[84:87], v[128:131], v[160:163], v[84:87]
	v_mfma_i32_16x16x64_i8 v[84:87], v[132:135], v[164:167], v[84:87]
	v_mfma_i32_16x16x64_i8 v[16:19], v[140:143], v[164:167], v[16:19]
	v_mfma_i32_16x16x64_i8 v[16:19], v[136:139], v[160:163], v[16:19]
	v_mfma_i32_16x16x64_i8 v[124:127], v[144:147], v[160:163], v[124:127]
	v_mfma_i32_16x16x64_i8 v[124:127], v[148:151], v[164:167], v[124:127]
	v_mfma_i32_16x16x64_i8 v[68:71], v[156:159], v[164:167], v[68:71]
	v_mfma_i32_16x16x64_i8 v[68:71], v[152:155], v[160:163], v[68:71]
	v_mfma_i32_16x16x64_i8 v[72:75], v[152:155], v[168:171], v[72:75]
	v_mfma_i32_16x16x64_i8 v[72:75], v[156:159], v[192:195], v[72:75]
	v_mfma_i32_16x16x64_i8 v[120:123], v[148:151], v[192:195], v[120:123]
	v_mfma_i32_16x16x64_i8 v[120:123], v[144:147], v[168:171], v[120:123]
	v_mfma_i32_16x16x64_i8 v[20:23], v[136:139], v[168:171], v[20:23]
	v_mfma_i32_16x16x64_i8 v[20:23], v[140:143], v[192:195], v[20:23]
	v_mfma_i32_16x16x64_i8 v[88:91], v[132:135], v[192:195], v[88:91]
	v_mfma_i32_16x16x64_i8 v[88:91], v[128:131], v[168:171], v[88:91]
	s_setprio 0
	s_setprio 1
	v_mfma_i32_16x16x64_i8 v[92:95], v[128:131], v[196:199], v[92:95]
	v_mfma_i32_16x16x64_i8 v[92:95], v[132:135], v[200:203], v[92:95]
	v_mfma_i32_16x16x64_i8 v[24:27], v[140:143], v[200:203], v[24:27]
	v_mfma_i32_16x16x64_i8 v[24:27], v[136:139], v[196:199], v[24:27]
	v_mfma_i32_16x16x64_i8 v[116:119], v[144:147], v[196:199], v[116:119]
	v_mfma_i32_16x16x64_i8 v[116:119], v[148:151], v[200:203], v[116:119]
	v_mfma_i32_16x16x64_i8 v[80:83], v[156:159], v[200:203], v[80:83]
	v_mfma_i32_16x16x64_i8 v[80:83], v[152:155], v[196:199], v[80:83]
	v_mfma_i32_16x16x64_i8 v[60:63], v[152:155], v[204:207], v[60:63]
	v_mfma_i32_16x16x64_i8 v[60:63], v[156:159], v[208:211], v[60:63]
	v_mfma_i32_16x16x64_i8 v[112:115], v[148:151], v[208:211], v[112:115]
	v_mfma_i32_16x16x64_i8 v[112:115], v[144:147], v[204:207], v[112:115]
	s_setprio 2
	s_barrier
	v_mfma_i32_16x16x64_i8 v[28:31], v[136:139], v[204:207], v[28:31]
	v_mfma_i32_16x16x64_i8 v[28:31], v[140:143], v[208:211], v[28:31]
	v_mfma_i32_16x16x64_i8 v[96:99], v[132:135], v[208:211], v[96:99]
	v_mfma_i32_16x16x64_i8 v[96:99], v[128:131], v[204:207], v[96:99]
	s_setprio 0
	s_add_i32 s9, s9, s33
	s_mov_b32 m0, s9
	ds_read_b128 v[160:163], v189 offset:49152
	ds_read_b128 v[164:167], v189 offset:50176
	ds_read_b128 v[168:171], v189 offset:51200
	ds_read_b128 v[192:195], v189 offset:52224
	ds_read_b128 v[196:199], v189 offset:53248
	ds_read_b128 v[200:203], v189 offset:54272
	ds_read_b128 v[204:207], v189 offset:55296
	ds_read_b128 v[208:211], v189 offset:56320
	s_add_u32 s98, s100, s44
	s_addc_u32 s99, s101, s45
	global_load_lds_dwordx4 v174, s[98:99]
	s_add_i32 m0, s9, 0x2000
	s_add_i32 s9, s50, s33
	s_add_u32 s98, s100, s46
	s_addc_u32 s99, s101, s47
	global_load_lds_dwordx4 v174, s[98:99]
	s_mov_b32 m0, s9
	s_add_u32 s98, s100, s48
	s_addc_u32 s99, s101, s49
	global_load_lds_dwordx4 v174, s[98:99]
	s_add_i32 m0, s9, 0x2000
	s_nop 0
	s_add_u32 s98, s100, s52
	s_addc_u32 s99, s101, s53
	global_load_lds_dwordx4 v174, s[98:99]
	s_mov_b32 m0, s90
	s_nop 0
	s_add_u32 s98, vcc_lo, s44
	s_addc_u32 s99, vcc_hi, s45
	global_load_lds_dwordx4 v172, s[98:99]
	s_mov_b32 m0, s91
	s_nop 0
	s_add_u32 s98, vcc_lo, s46
	s_addc_u32 s99, vcc_hi, s47
	global_load_lds_dwordx4 v172, s[98:99]
	s_waitcnt vmcnt(8)
	s_waitcnt lgkmcnt(0)
	s_barrier
	s_setprio 1
	s_waitcnt lgkmcnt(0)
	v_mfma_i32_16x16x64_i8 v[48:51], v[128:131], v[160:163], v[48:51]
	v_mfma_i32_16x16x64_i8 v[48:51], v[132:135], v[164:167], v[48:51]
	v_mfma_i32_16x16x64_i8 v[0:3], v[140:143], v[164:167], v[0:3]
	v_mfma_i32_16x16x64_i8 v[0:3], v[136:139], v[160:163], v[0:3]
	v_mfma_i32_16x16x64_i8 v[108:111], v[144:147], v[160:163], v[108:111]
	v_mfma_i32_16x16x64_i8 v[108:111], v[148:151], v[164:167], v[108:111]
	v_mfma_i32_16x16x64_i8 v[44:47], v[156:159], v[164:167], v[44:47]
	v_mfma_i32_16x16x64_i8 v[44:47], v[152:155], v[160:163], v[44:47]
	v_mfma_i32_16x16x64_i8 v[40:43], v[152:155], v[168:171], v[40:43]
	v_mfma_i32_16x16x64_i8 v[40:43], v[156:159], v[192:195], v[40:43]
	v_mfma_i32_16x16x64_i8 v[104:107], v[148:151], v[192:195], v[104:107]
	v_mfma_i32_16x16x64_i8 v[104:107], v[144:147], v[168:171], v[104:107]
	v_mfma_i32_16x16x64_i8 v[4:7], v[136:139], v[168:171], v[4:7]
	v_mfma_i32_16x16x64_i8 v[4:7], v[140:143], v[192:195], v[4:7]
	v_mfma_i32_16x16x64_i8 v[52:55], v[132:135], v[192:195], v[52:55]
	v_mfma_i32_16x16x64_i8 v[52:55], v[128:131], v[168:171], v[52:55]
	s_setprio 0
	s_setprio 1
	v_mfma_i32_16x16x64_i8 v[56:59], v[128:131], v[196:199], v[56:59]
	v_mfma_i32_16x16x64_i8 v[56:59], v[132:135], v[200:203], v[56:59]
	v_mfma_i32_16x16x64_i8 v[8:11], v[140:143], v[200:203], v[8:11]
	v_mfma_i32_16x16x64_i8 v[8:11], v[136:139], v[196:199], v[8:11]
	v_mfma_i32_16x16x64_i8 v[100:103], v[144:147], v[196:199], v[100:103]
	v_mfma_i32_16x16x64_i8 v[100:103], v[148:151], v[200:203], v[100:103]
	v_mfma_i32_16x16x64_i8 v[32:35], v[156:159], v[200:203], v[32:35]
	v_mfma_i32_16x16x64_i8 v[32:35], v[152:155], v[196:199], v[32:35]
	v_mfma_i32_16x16x64_i8 v[36:39], v[152:155], v[204:207], v[36:39]
	v_mfma_i32_16x16x64_i8 v[36:39], v[156:159], v[208:211], v[36:39]
	v_mfma_i32_16x16x64_i8 v[76:79], v[148:151], v[208:211], v[76:79]
	v_mfma_i32_16x16x64_i8 v[76:79], v[144:147], v[204:207], v[76:79]
	s_setprio 2
	s_barrier
	v_mfma_i32_16x16x64_i8 v[12:15], v[136:139], v[204:207], v[12:15]
	v_mfma_i32_16x16x64_i8 v[12:15], v[140:143], v[208:211], v[12:15]
	v_mfma_i32_16x16x64_i8 v[64:67], v[132:135], v[208:211], v[64:67]
	v_mfma_i32_16x16x64_i8 v[64:67], v[128:131], v[204:207], v[64:67]
	s_setprio 0
	s_add_i32 s8, s8, 2
	s_add_u32 s75, s75, 0x100
	s_addc_u32 s78, s78, 0
	s_add_u32 s6, s6, 0x100
	s_addc_u32 s7, s7, 0
	s_cmp_gt_u32 s8, 29
	s_cbranch_scc0 .LBB0_800
	s_and_b64 vcc, exec, s[54:55]
	s_cbranch_vccz .LBB0_803
	s_barrier

.LBB0_1034:
	ds_read_b128 v[138:141], v151
	ds_read_b128 v[142:145], v151 offset:1024
	ds_read_b128 v[146:149], v151 offset:2048
	ds_read_b128 v[154:157], v151 offset:3072
	ds_read_b128 v[158:161], v152
	ds_read_b128 v[162:165], v152 offset:1024
	ds_read_b128 v[166:169], v152 offset:2048
	ds_read_b128 v[170:173], v152 offset:3072
	s_add_u32 s47, s44, 0xffd50080
	s_addc_u32 s64, s45, -1
	s_cmpk_eq_i32 s46, 0xa8
	s_cselect_b32 s65, s5, s64
	s_cselect_b32 s64, s4, s47
	s_cselect_b32 s67, s43, s63
	s_cselect_b32 s66, s42, s62
	s_add_i32 m0, s25, 0xc000
	ds_read_b128 v[174:177], v153
	ds_read_b128 v[178:181], v153 offset:1024
	ds_read_b128 v[182:185], v153 offset:2048
	ds_read_b128 v[186:189], v153 offset:3072
	ds_read_b128 v[190:193], v153 offset:4096
	ds_read_b128 v[194:197], v153 offset:5120
	ds_read_b128 v[198:201], v153 offset:6144
	ds_read_b128 v[202:205], v153 offset:7168
	global_load_lds_dwordx4 v132, s[44:45]
	s_add_i32 m0, s25, 0xe000
	s_nop 0
	s_add_u32 s98, s44, s0
	s_addc_u32 s99, s45, s1
	global_load_lds_dwordx4 v132, s[98:99]
	s_waitcnt vmcnt(8)
	s_waitcnt lgkmcnt(0)
	s_barrier
	s_setprio 1
	s_waitcnt lgkmcnt(0)
	v_mfma_f32_16x16x32_bf16 v[124:127], v[138:141], v[174:177], v[124:127]
	v_mfma_f32_16x16x32_bf16 v[124:127], v[142:145], v[178:181], v[124:127]
	v_mfma_f32_16x16x32_bf16 v[120:123], v[154:157], v[178:181], v[120:123]
	v_mfma_f32_16x16x32_bf16 v[120:123], v[146:149], v[174:177], v[120:123]
	v_mfma_f32_16x16x32_bf16 v[92:95], v[158:161], v[174:177], v[92:95]
	v_mfma_f32_16x16x32_bf16 v[92:95], v[162:165], v[178:181], v[92:95]
	v_mfma_f32_16x16x32_bf16 v[88:91], v[170:173], v[178:181], v[88:91]
	v_mfma_f32_16x16x32_bf16 v[88:91], v[166:169], v[174:177], v[88:91]
	v_mfma_f32_16x16x32_bf16 v[80:83], v[166:169], v[182:185], v[80:83]
	v_mfma_f32_16x16x32_bf16 v[80:83], v[170:173], v[186:189], v[80:83]
	v_mfma_f32_16x16x32_bf16 v[84:87], v[162:165], v[186:189], v[84:87]
	v_mfma_f32_16x16x32_bf16 v[84:87], v[158:161], v[182:185], v[84:87]
	v_mfma_f32_16x16x32_bf16 v[112:115], v[146:149], v[182:185], v[112:115]
	v_mfma_f32_16x16x32_bf16 v[112:115], v[154:157], v[186:189], v[112:115]
	v_mfma_f32_16x16x32_bf16 v[116:119], v[142:145], v[186:189], v[116:119]
	v_mfma_f32_16x16x32_bf16 v[116:119], v[138:141], v[182:185], v[116:119]
	s_setprio 0
	s_setprio 1
	v_mfma_f32_16x16x32_bf16 v[108:111], v[138:141], v[190:193], v[108:111]
	v_mfma_f32_16x16x32_bf16 v[108:111], v[142:145], v[194:197], v[108:111]
	v_mfma_f32_16x16x32_bf16 v[104:107], v[154:157], v[194:197], v[104:107]
	v_mfma_f32_16x16x32_bf16 v[104:107], v[146:149], v[190:193], v[104:107]
	v_mfma_f32_16x16x32_bf16 v[76:79], v[158:161], v[190:193], v[76:79]
	v_mfma_f32_16x16x32_bf16 v[76:79], v[162:165], v[194:197], v[76:79]
	v_mfma_f32_16x16x32_bf16 v[72:75], v[170:173], v[194:197], v[72:75]
	v_mfma_f32_16x16x32_bf16 v[72:75], v[166:169], v[190:193], v[72:75]
	v_mfma_f32_16x16x32_bf16 v[64:67], v[166:169], v[198:201], v[64:67]
	v_mfma_f32_16x16x32_bf16 v[64:67], v[170:173], v[202:205], v[64:67]
	v_mfma_f32_16x16x32_bf16 v[68:71], v[162:165], v[202:205], v[68:71]
	v_mfma_f32_16x16x32_bf16 v[68:71], v[158:161], v[198:201], v[68:71]
	s_setprio 2
	s_barrier
	v_mfma_f32_16x16x32_bf16 v[96:99], v[146:149], v[198:201], v[96:99]
	v_mfma_f32_16x16x32_bf16 v[96:99], v[154:157], v[202:205], v[96:99]
	v_mfma_f32_16x16x32_bf16 v[100:103], v[142:145], v[202:205], v[100:103]
	v_mfma_f32_16x16x32_bf16 v[100:103], v[138:141], v[198:201], v[100:103]
	s_setprio 0
	s_add_i32 s47, s56, s24
	s_mov_b32 m0, s47
	ds_read_b128 v[174:177], v153 offset:16384
	ds_read_b128 v[178:181], v153 offset:17408
	ds_read_b128 v[182:185], v153 offset:18432
	ds_read_b128 v[186:189], v153 offset:19456
	ds_read_b128 v[190:193], v153 offset:20480
	ds_read_b128 v[194:197], v153 offset:21504
	ds_read_b128 v[198:201], v153 offset:22528
	ds_read_b128 v[202:205], v153 offset:23552
	global_load_lds_dwordx4 v130, s[66:67]
	s_add_i32 m0, s47, 0x2000
	s_add_i32 s47, s57, s24
	s_add_u32 s98, s66, s0
	s_addc_u32 s99, s67, s1
	global_load_lds_dwordx4 v130, s[98:99]
	s_mov_b32 m0, s47
	s_nop 0
	s_add_u32 s98, s66, s6
	s_addc_u32 s99, s67, s7
	global_load_lds_dwordx4 v130, s[98:99]
	s_add_i32 m0, s47, 0x2000
	s_nop 0
	s_add_u32 s98, s66, s8
	s_addc_u32 s99, s67, s9
	global_load_lds_dwordx4 v130, s[98:99]
	s_mov_b64 s[100:101], s[64:65]
	s_mov_b32 m0, s25
	s_nop 0
	global_load_lds_dwordx4 v128, s[64:65]
	s_mov_b32 m0, s33
	s_nop 0
	s_add_u32 s98, s64, s0
	s_addc_u32 s99, s65, s1
	global_load_lds_dwordx4 v128, s[98:99]
	s_waitcnt vmcnt(8)
	s_waitcnt lgkmcnt(0)
	s_barrier
	s_setprio 1
	s_waitcnt lgkmcnt(0)
	v_mfma_f32_16x16x32_bf16 v[60:63], v[138:141], v[174:177], v[60:63]
	v_mfma_f32_16x16x32_bf16 v[60:63], v[142:145], v[178:181], v[60:63]
	v_mfma_f32_16x16x32_bf16 v[56:59], v[154:157], v[178:181], v[56:59]
	v_mfma_f32_16x16x32_bf16 v[56:59], v[146:149], v[174:177], v[56:59]
	v_mfma_f32_16x16x32_bf16 v[28:31], v[158:161], v[174:177], v[28:31]
	v_mfma_f32_16x16x32_bf16 v[28:31], v[162:165], v[178:181], v[28:31]
	v_mfma_f32_16x16x32_bf16 v[24:27], v[170:173], v[178:181], v[24:27]
	v_mfma_f32_16x16x32_bf16 v[24:27], v[166:169], v[174:177], v[24:27]
	v_mfma_f32_16x16x32_bf16 v[16:19], v[166:169], v[182:185], v[16:19]
	v_mfma_f32_16x16x32_bf16 v[16:19], v[170:173], v[186:189], v[16:19]
	v_mfma_f32_16x16x32_bf16 v[20:23], v[162:165], v[186:189], v[20:23]
	v_mfma_f32_16x16x32_bf16 v[20:23], v[158:161], v[182:185], v[20:23]
	v_mfma_f32_16x16x32_bf16 v[48:51], v[146:149], v[182:185], v[48:51]
	v_mfma_f32_16x16x32_bf16 v[48:51], v[154:157], v[186:189], v[48:51]
	v_mfma_f32_16x16x32_bf16 v[52:55], v[142:145], v[186:189], v[52:55]
	v_mfma_f32_16x16x32_bf16 v[52:55], v[138:141], v[182:185], v[52:55]
	s_setprio 0
	s_setprio 1
	v_mfma_f32_16x16x32_bf16 v[44:47], v[138:141], v[190:193], v[44:47]
	v_mfma_f32_16x16x32_bf16 v[44:47], v[142:145], v[194:197], v[44:47]
	v_mfma_f32_16x16x32_bf16 v[40:43], v[154:157], v[194:197], v[40:43]
	v_mfma_f32_16x16x32_bf16 v[40:43], v[146:149], v[190:193], v[40:43]
	v_mfma_f32_16x16x32_bf16 v[12:15], v[158:161], v[190:193], v[12:15]
	v_mfma_f32_16x16x32_bf16 v[12:15], v[162:165], v[194:197], v[12:15]
	v_mfma_f32_16x16x32_bf16 v[8:11], v[170:173], v[194:197], v[8:11]
	v_mfma_f32_16x16x32_bf16 v[8:11], v[166:169], v[190:193], v[8:11]
	v_mfma_f32_16x16x32_bf16 v[0:3], v[166:169], v[198:201], v[0:3]
	v_mfma_f32_16x16x32_bf16 v[0:3], v[170:173], v[202:205], v[0:3]
	v_mfma_f32_16x16x32_bf16 v[4:7], v[162:165], v[202:205], v[4:7]
	v_mfma_f32_16x16x32_bf16 v[4:7], v[158:161], v[198:201], v[4:7]
	s_setprio 2
	s_barrier
	v_mfma_f32_16x16x32_bf16 v[32:35], v[146:149], v[198:201], v[32:35]
	v_mfma_f32_16x16x32_bf16 v[32:35], v[154:157], v[202:205], v[32:35]
	v_mfma_f32_16x16x32_bf16 v[36:39], v[142:145], v[202:205], v[36:39]
	v_mfma_f32_16x16x32_bf16 v[36:39], v[138:141], v[198:201], v[36:39]
	s_setprio 0
	s_add_i32 s47, 0, 0x18000
	s_add_i32 s64, 0, 0x1c000
	v_add_u32_e32 v154, s47, v150
	v_add_u32_e32 v170, s64, v150
	ds_read_b128 v[138:141], v154
	ds_read_b128 v[142:145], v154 offset:1024
	ds_read_b128 v[146:149], v154 offset:2048
	ds_read_b128 v[154:157], v154 offset:3072
	ds_read_b128 v[158:161], v170
	ds_read_b128 v[162:165], v170 offset:1024
	ds_read_b128 v[166:169], v170 offset:2048
	ds_read_b128 v[170:173], v170 offset:3072
	s_mov_b32 m0, s48
	ds_read_b128 v[174:177], v153 offset:32768
	ds_read_b128 v[178:181], v153 offset:33792
	ds_read_b128 v[182:185], v153 offset:34816
	ds_read_b128 v[186:189], v153 offset:35840
	ds_read_b128 v[190:193], v153 offset:36864
	ds_read_b128 v[194:197], v153 offset:37888
	ds_read_b128 v[198:201], v153 offset:38912
	ds_read_b128 v[202:205], v153 offset:39936
	s_add_u32 s98, s100, s6
	s_addc_u32 s99, s101, s7
	global_load_lds_dwordx4 v128, s[98:99]
	s_mov_b32 m0, s49
	s_nop 0
	s_add_u32 s98, s100, s8
	s_addc_u32 s99, s101, s9
	global_load_lds_dwordx4 v128, s[98:99]
	s_waitcnt vmcnt(8)
	s_waitcnt lgkmcnt(0)
	s_barrier
	s_setprio 1
	s_waitcnt lgkmcnt(0)
	v_mfma_f32_16x16x32_bf16 v[124:127], v[138:141], v[174:177], v[124:127]
	v_mfma_f32_16x16x32_bf16 v[124:127], v[142:145], v[178:181], v[124:127]
	v_mfma_f32_16x16x32_bf16 v[120:123], v[154:157], v[178:181], v[120:123]
	v_mfma_f32_16x16x32_bf16 v[120:123], v[146:149], v[174:177], v[120:123]
	v_mfma_f32_16x16x32_bf16 v[92:95], v[158:161], v[174:177], v[92:95]
	v_mfma_f32_16x16x32_bf16 v[92:95], v[162:165], v[178:181], v[92:95]
	v_mfma_f32_16x16x32_bf16 v[88:91], v[170:173], v[178:181], v[88:91]
	v_mfma_f32_16x16x32_bf16 v[88:91], v[166:169], v[174:177], v[88:91]
	v_mfma_f32_16x16x32_bf16 v[80:83], v[166:169], v[182:185], v[80:83]
	v_mfma_f32_16x16x32_bf16 v[80:83], v[170:173], v[186:189], v[80:83]
	v_mfma_f32_16x16x32_bf16 v[84:87], v[162:165], v[186:189], v[84:87]
	v_mfma_f32_16x16x32_bf16 v[84:87], v[158:161], v[182:185], v[84:87]
	v_mfma_f32_16x16x32_bf16 v[112:115], v[146:149], v[182:185], v[112:115]
	v_mfma_f32_16x16x32_bf16 v[112:115], v[154:157], v[186:189], v[112:115]
	v_mfma_f32_16x16x32_bf16 v[116:119], v[142:145], v[186:189], v[116:119]
	v_mfma_f32_16x16x32_bf16 v[116:119], v[138:141], v[182:185], v[116:119]
	s_setprio 0
	s_setprio 1
	v_mfma_f32_16x16x32_bf16 v[108:111], v[138:141], v[190:193], v[108:111]
	v_mfma_f32_16x16x32_bf16 v[108:111], v[142:145], v[194:197], v[108:111]
	v_mfma_f32_16x16x32_bf16 v[104:107], v[154:157], v[194:197], v[104:107]
	v_mfma_f32_16x16x32_bf16 v[104:107], v[146:149], v[190:193], v[104:107]
	v_mfma_f32_16x16x32_bf16 v[76:79], v[158:161], v[190:193], v[76:79]
	v_mfma_f32_16x16x32_bf16 v[76:79], v[162:165], v[194:197], v[76:79]
	v_mfma_f32_16x16x32_bf16 v[72:75], v[170:173], v[194:197], v[72:75]
	v_mfma_f32_16x16x32_bf16 v[72:75], v[166:169], v[190:193], v[72:75]
	v_mfma_f32_16x16x32_bf16 v[64:67], v[166:169], v[198:201], v[64:67]
	v_mfma_f32_16x16x32_bf16 v[64:67], v[170:173], v[202:205], v[64:67]
	v_mfma_f32_16x16x32_bf16 v[68:71], v[162:165], v[202:205], v[68:71]
	v_mfma_f32_16x16x32_bf16 v[68:71], v[158:161], v[198:201], v[68:71]
	s_setprio 2
	s_barrier
	v_mfma_f32_16x16x32_bf16 v[96:99], v[146:149], v[198:201], v[96:99]
	v_mfma_f32_16x16x32_bf16 v[96:99], v[154:157], v[202:205], v[96:99]
	v_mfma_f32_16x16x32_bf16 v[100:103], v[142:145], v[202:205], v[100:103]
	v_mfma_f32_16x16x32_bf16 v[100:103], v[138:141], v[198:201], v[100:103]
	s_setprio 0
	s_add_i32 s47, s47, s24
	s_mov_b32 m0, s47
	ds_read_b128 v[174:177], v153 offset:49152
	ds_read_b128 v[178:181], v153 offset:50176
	ds_read_b128 v[182:185], v153 offset:51200
	ds_read_b128 v[186:189], v153 offset:52224
	ds_read_b128 v[190:193], v153 offset:53248
	ds_read_b128 v[194:197], v153 offset:54272
	ds_read_b128 v[198:201], v153 offset:55296
	ds_read_b128 v[202:205], v153 offset:56320
	s_add_u32 s98, s66, s16
	s_addc_u32 s99, s67, s17
	global_load_lds_dwordx4 v130, s[98:99]
	s_add_i32 m0, s47, 0x2000
	s_add_i32 s47, s64, s24
	s_add_u32 s98, s66, s20
	s_addc_u32 s99, s67, s21
	global_load_lds_dwordx4 v130, s[98:99]
	s_mov_b32 m0, s47
	s_add_u32 s98, s66, s34
	s_addc_u32 s99, s67, s35
	global_load_lds_dwordx4 v130, s[98:99]
	s_add_i32 m0, s47, 0x2000
	s_nop 0
	s_add_u32 s98, s66, s36
	s_addc_u32 s99, s67, s37
	global_load_lds_dwordx4 v130, s[98:99]
	s_mov_b32 m0, s51
	s_nop 0
	s_add_u32 s98, s100, s16
	s_addc_u32 s99, s101, s17
	global_load_lds_dwordx4 v128, s[98:99]
	s_mov_b32 m0, s52
	s_nop 0
	s_add_u32 s98, s100, s20
	s_addc_u32 s99, s101, s21
	global_load_lds_dwordx4 v128, s[98:99]
	s_waitcnt vmcnt(8)
	s_waitcnt lgkmcnt(0)
	s_barrier
	s_setprio 1
	s_waitcnt lgkmcnt(0)
	v_mfma_f32_16x16x32_bf16 v[60:63], v[138:141], v[174:177], v[60:63]
	v_mfma_f32_16x16x32_bf16 v[60:63], v[142:145], v[178:181], v[60:63]
	v_mfma_f32_16x16x32_bf16 v[56:59], v[154:157], v[178:181], v[56:59]
	v_mfma_f32_16x16x32_bf16 v[56:59], v[146:149], v[174:177], v[56:59]
	v_mfma_f32_16x16x32_bf16 v[28:31], v[158:161], v[174:177], v[28:31]
	v_mfma_f32_16x16x32_bf16 v[28:31], v[162:165], v[178:181], v[28:31]
	v_mfma_f32_16x16x32_bf16 v[24:27], v[170:173], v[178:181], v[24:27]
	v_mfma_f32_16x16x32_bf16 v[24:27], v[166:169], v[174:177], v[24:27]
	v_mfma_f32_16x16x32_bf16 v[16:19], v[166:169], v[182:185], v[16:19]
	v_mfma_f32_16x16x32_bf16 v[16:19], v[170:173], v[186:189], v[16:19]
	v_mfma_f32_16x16x32_bf16 v[20:23], v[162:165], v[186:189], v[20:23]
	v_mfma_f32_16x16x32_bf16 v[20:23], v[158:161], v[182:185], v[20:23]
	v_mfma_f32_16x16x32_bf16 v[48:51], v[146:149], v[182:185], v[48:51]
	v_mfma_f32_16x16x32_bf16 v[48:51], v[154:157], v[186:189], v[48:51]
	v_mfma_f32_16x16x32_bf16 v[52:55], v[142:145], v[186:189], v[52:55]
	v_mfma_f32_16x16x32_bf16 v[52:55], v[138:141], v[182:185], v[52:55]
	s_setprio 0
	s_setprio 1
	v_mfma_f32_16x16x32_bf16 v[44:47], v[138:141], v[190:193], v[44:47]
	v_mfma_f32_16x16x32_bf16 v[44:47], v[142:145], v[194:197], v[44:47]
	v_mfma_f32_16x16x32_bf16 v[40:43], v[154:157], v[194:197], v[40:43]
	v_mfma_f32_16x16x32_bf16 v[40:43], v[146:149], v[190:193], v[40:43]
	v_mfma_f32_16x16x32_bf16 v[12:15], v[158:161], v[190:193], v[12:15]
	v_mfma_f32_16x16x32_bf16 v[12:15], v[162:165], v[194:197], v[12:15]
	v_mfma_f32_16x16x32_bf16 v[8:11], v[170:173], v[194:197], v[8:11]
	v_mfma_f32_16x16x32_bf16 v[8:11], v[166:169], v[190:193], v[8:11]
	v_mfma_f32_16x16x32_bf16 v[0:3], v[166:169], v[198:201], v[0:3]
	v_mfma_f32_16x16x32_bf16 v[0:3], v[170:173], v[202:205], v[0:3]
	v_mfma_f32_16x16x32_bf16 v[4:7], v[162:165], v[202:205], v[4:7]
	v_mfma_f32_16x16x32_bf16 v[4:7], v[158:161], v[198:201], v[4:7]
	s_setprio 2
	s_barrier
	v_mfma_f32_16x16x32_bf16 v[32:35], v[146:149], v[198:201], v[32:35]
	v_mfma_f32_16x16x32_bf16 v[32:35], v[154:157], v[202:205], v[32:35]
	v_mfma_f32_16x16x32_bf16 v[36:39], v[142:145], v[202:205], v[36:39]
	v_mfma_f32_16x16x32_bf16 v[36:39], v[138:141], v[198:201], v[36:39]
	s_setprio 0
	s_add_i32 s46, s46, 2
	s_add_u32 s62, s62, 0x100
	s_addc_u32 s63, s63, 0
	s_add_u32 s44, s44, 0x100
	s_addc_u32 s45, s45, 0
	s_cmpk_gt_u32 s46, 0xa9
	s_cbranch_scc0 .LBB0_1034
	s_and_b64 vcc, exec, s[38:39]
	s_cbranch_vccz .LBB0_1037
	s_barrier

.LBB0_1180:
	ds_read_b128 v[112:115], v181
	ds_read_b128 v[116:119], v181 offset:1024
	ds_read_b128 v[128:131], v181 offset:2048
	ds_read_b128 v[142:145], v181 offset:3072
	ds_read_b128 v[146:149], v202
	ds_read_b128 v[150:153], v202 offset:1024
	ds_read_b128 v[154:157], v202 offset:2048
	ds_read_b128 v[168:171], v202 offset:3072
	s_add_u32 s49, s46, 0xfff80080
	s_addc_u32 s70, s47, -1
	s_cmp_eq_u32 s48, 28
	s_cselect_b32 s71, s39, s70
	s_cselect_b32 s70, s66, s49
	s_cselect_b32 s73, s37, s69
	s_cselect_b32 s72, s67, s68
	s_add_i32 m0, s45, 0xc000
	ds_read_b128 v[172:175], v203
	ds_read_b128 v[182:185], v203 offset:1024
	ds_read_b128 v[186:189], v203 offset:2048
	ds_read_b128 v[190:193], v203 offset:3072
	ds_read_b128 v[194:197], v203 offset:4096
	ds_read_b128 v[198:201], v203 offset:5120
	ds_read_b128 v[206:209], v203 offset:6144
	ds_read_b128 v[210:213], v203 offset:7168
	global_load_lds_dwordx4 v162, s[46:47]
	s_add_i32 m0, s45, 0xe000
	s_nop 0
	s_add_u32 s98, s46, s2
	s_addc_u32 s99, s47, s3
	global_load_lds_dwordx4 v162, s[98:99]
	s_waitcnt vmcnt(8)
	s_waitcnt lgkmcnt(0)
	s_barrier
	s_setprio 1
	s_waitcnt lgkmcnt(0)
	v_mfma_i32_16x16x64_i8 v[138:141], v[112:115], v[172:175], v[138:141]
	v_mfma_i32_16x16x64_i8 v[132:135], v[128:131], v[172:175], v[134:137]
	v_mfma_i32_16x16x64_i8 v[124:127], v[112:115], v[186:189], v[124:127]
	v_mfma_i32_16x16x64_i8 v[120:123], v[128:131], v[186:189], v[120:123]
	v_mfma_i32_16x16x64_i8 v[108:111], v[112:115], v[194:197], v[108:111]
	v_mfma_i32_16x16x64_i8 v[104:107], v[128:131], v[194:197], v[104:107]
	v_mfma_i32_16x16x64_i8 v[100:103], v[112:115], v[206:209], v[100:103]
	v_mfma_i32_16x16x64_i8 v[96:99], v[128:131], v[206:209], v[96:99]
	v_mfma_i32_16x16x64_i8 v[138:141], v[116:119], v[182:185], v[138:141]
	v_mfma_i32_16x16x64_i8 v[132:135], v[142:145], v[182:185], v[132:135]
	v_mfma_i32_16x16x64_i8 v[124:127], v[116:119], v[190:193], v[124:127]
	v_mfma_i32_16x16x64_i8 v[120:123], v[142:145], v[190:193], v[120:123]
	v_mfma_i32_16x16x64_i8 v[108:111], v[116:119], v[198:201], v[108:111]
	v_mfma_i32_16x16x64_i8 v[104:107], v[142:145], v[198:201], v[104:107]
	v_mfma_i32_16x16x64_i8 v[100:103], v[116:119], v[210:213], v[100:103]
	v_mfma_i32_16x16x64_i8 v[96:99], v[142:145], v[210:213], v[96:99]
	s_setprio 0
	s_setprio 1
	v_mfma_i32_16x16x64_i8 v[60:63], v[146:149], v[172:175], v[60:63]
	v_mfma_i32_16x16x64_i8 v[60:63], v[150:153], v[182:185], v[60:63]
	v_mfma_i32_16x16x64_i8 v[56:59], v[154:157], v[172:175], v[56:59]
	v_mfma_i32_16x16x64_i8 v[56:59], v[168:171], v[182:185], v[56:59]
	v_mfma_i32_16x16x64_i8 v[52:55], v[146:149], v[186:189], v[52:55]
	v_mfma_i32_16x16x64_i8 v[52:55], v[150:153], v[190:193], v[52:55]
	v_mfma_i32_16x16x64_i8 v[48:51], v[154:157], v[186:189], v[48:51]
	v_mfma_i32_16x16x64_i8 v[48:51], v[168:171], v[190:193], v[48:51]
	v_mfma_i32_16x16x64_i8 v[44:47], v[146:149], v[194:197], v[44:47]
	v_mfma_i32_16x16x64_i8 v[44:47], v[150:153], v[198:201], v[44:47]
	v_mfma_i32_16x16x64_i8 v[40:43], v[154:157], v[194:197], v[40:43]
	v_mfma_i32_16x16x64_i8 v[40:43], v[168:171], v[198:201], v[40:43]
	s_setprio 2
	s_barrier
	v_mfma_i32_16x16x64_i8 v[36:39], v[146:149], v[206:209], v[36:39]
	v_mfma_i32_16x16x64_i8 v[36:39], v[150:153], v[210:213], v[36:39]
	v_mfma_i32_16x16x64_i8 v[32:35], v[154:157], v[206:209], v[32:35]
	v_mfma_i32_16x16x64_i8 v[32:35], v[168:171], v[210:213], v[32:35]
	s_setprio 0
	s_add_i32 s49, s61, s33
	s_mov_b32 m0, s49
	ds_read_b128 v[172:175], v203 offset:16384
	ds_read_b128 v[182:185], v203 offset:17408
	ds_read_b128 v[186:189], v203 offset:18432
	ds_read_b128 v[190:193], v203 offset:19456
	ds_read_b128 v[194:197], v203 offset:20480
	ds_read_b128 v[198:201], v203 offset:21504
	ds_read_b128 v[206:209], v203 offset:22528
	ds_read_b128 v[210:213], v203 offset:23552
	global_load_lds_dwordx4 v160, s[72:73]
	s_add_i32 m0, s49, 0x2000
	s_add_i32 s49, s62, s33
	s_add_u32 s98, s72, s2
	s_addc_u32 s99, s73, s3
	global_load_lds_dwordx4 v160, s[98:99]
	s_mov_b32 m0, s49
	s_mov_b64 s[100:101], s[70:71]
	s_add_u32 s98, s72, s6
	s_addc_u32 s99, s73, s7
	global_load_lds_dwordx4 v160, s[98:99]
	s_add_i32 m0, s49, 0x2000
	s_nop 0
	s_add_u32 s98, s72, s8
	s_addc_u32 s99, s73, s9
	global_load_lds_dwordx4 v160, s[98:99]
	s_mov_b32 m0, s45
	s_nop 0
	global_load_lds_dwordx4 v158, s[70:71]
	s_mov_b32 m0, s50
	s_nop 0
	s_add_u32 s98, s70, s2
	s_addc_u32 s99, s71, s3
	global_load_lds_dwordx4 v158, s[98:99]
	s_waitcnt vmcnt(8)
	s_waitcnt lgkmcnt(0)
	s_barrier
	s_setprio 1
	s_waitcnt lgkmcnt(0)
	v_mfma_i32_16x16x64_i8 v[92:95], v[112:115], v[172:175], v[92:95]
	v_mfma_i32_16x16x64_i8 v[92:95], v[116:119], v[182:185], v[92:95]
	v_mfma_i32_16x16x64_i8 v[88:91], v[142:145], v[182:185], v[88:91]
	v_mfma_i32_16x16x64_i8 v[88:91], v[128:131], v[172:175], v[88:91]
	v_mfma_i32_16x16x64_i8 v[28:31], v[146:149], v[172:175], v[28:31]
	v_mfma_i32_16x16x64_i8 v[28:31], v[150:153], v[182:185], v[28:31]
	v_mfma_i32_16x16x64_i8 v[24:27], v[168:171], v[182:185], v[24:27]
	v_mfma_i32_16x16x64_i8 v[24:27], v[154:157], v[172:175], v[24:27]
	v_mfma_i32_16x16x64_i8 v[16:19], v[154:157], v[186:189], v[16:19]
	v_mfma_i32_16x16x64_i8 v[16:19], v[168:171], v[190:193], v[16:19]
	v_mfma_i32_16x16x64_i8 v[20:23], v[150:153], v[190:193], v[20:23]
	v_mfma_i32_16x16x64_i8 v[20:23], v[146:149], v[186:189], v[20:23]
	v_mfma_i32_16x16x64_i8 v[80:83], v[128:131], v[186:189], v[80:83]
	v_mfma_i32_16x16x64_i8 v[80:83], v[142:145], v[190:193], v[80:83]
	v_mfma_i32_16x16x64_i8 v[84:87], v[116:119], v[190:193], v[84:87]
	v_mfma_i32_16x16x64_i8 v[84:87], v[112:115], v[186:189], v[84:87]
	s_setprio 0
	s_setprio 1
	v_mfma_i32_16x16x64_i8 v[76:79], v[112:115], v[194:197], v[76:79]
	v_mfma_i32_16x16x64_i8 v[76:79], v[116:119], v[198:201], v[76:79]
	v_mfma_i32_16x16x64_i8 v[72:75], v[142:145], v[198:201], v[72:75]
	v_mfma_i32_16x16x64_i8 v[72:75], v[128:131], v[194:197], v[72:75]
	v_mfma_i32_16x16x64_i8 v[12:15], v[146:149], v[194:197], v[12:15]
	v_mfma_i32_16x16x64_i8 v[12:15], v[150:153], v[198:201], v[12:15]
	v_mfma_i32_16x16x64_i8 v[8:11], v[168:171], v[198:201], v[8:11]
	v_mfma_i32_16x16x64_i8 v[8:11], v[154:157], v[194:197], v[8:11]
	v_mfma_i32_16x16x64_i8 v[0:3], v[154:157], v[206:209], v[0:3]
	v_mfma_i32_16x16x64_i8 v[0:3], v[168:171], v[210:213], v[0:3]
	v_mfma_i32_16x16x64_i8 v[4:7], v[150:153], v[210:213], v[4:7]
	v_mfma_i32_16x16x64_i8 v[4:7], v[146:149], v[206:209], v[4:7]
	s_setprio 2
	s_barrier
	v_mfma_i32_16x16x64_i8 v[64:67], v[128:131], v[206:209], v[64:67]
	v_mfma_i32_16x16x64_i8 v[64:67], v[142:145], v[210:213], v[64:67]
	v_mfma_i32_16x16x64_i8 v[68:71], v[116:119], v[210:213], v[68:71]
	v_mfma_i32_16x16x64_i8 v[68:71], v[112:115], v[206:209], v[68:71]
	s_setprio 0
	s_add_i32 s49, 0, 0x18000
	v_add_u32_e32 v136, s49, v179
	s_add_i32 s70, 0, 0x1c000
	ds_read_b128 v[112:115], v136
	ds_read_b128 v[116:119], v136 offset:1024
	ds_read_b128 v[128:131], v136 offset:2048
	ds_read_b128 v[142:145], v136 offset:3072
	v_add_u32_e32 v136, s70, v179
	ds_read_b128 v[146:149], v136
	ds_read_b128 v[150:153], v136 offset:1024
	ds_read_b128 v[154:157], v136 offset:2048
	ds_read_b128 v[168:171], v136 offset:3072
	s_mov_b32 m0, s51
	ds_read_b128 v[172:175], v203 offset:32768
	ds_read_b128 v[182:185], v203 offset:33792
	ds_read_b128 v[186:189], v203 offset:34816
	ds_read_b128 v[190:193], v203 offset:35840
	ds_read_b128 v[194:197], v203 offset:36864
	ds_read_b128 v[198:201], v203 offset:37888
	ds_read_b128 v[206:209], v203 offset:38912
	ds_read_b128 v[210:213], v203 offset:39936
	s_add_u32 s98, s100, s6
	s_addc_u32 s99, s101, s7
	global_load_lds_dwordx4 v158, s[98:99]
	s_mov_b32 m0, s52
	s_nop 0
	s_add_u32 s98, s100, s8
	s_addc_u32 s99, s101, s9
	global_load_lds_dwordx4 v158, s[98:99]
	s_waitcnt vmcnt(8)
	s_waitcnt lgkmcnt(0)
	s_barrier
	s_setprio 1
	s_waitcnt lgkmcnt(0)
	v_mfma_i32_16x16x64_i8 v[136:139], v[112:115], v[172:175], v[138:141]
	v_mfma_i32_16x16x64_i8 v[132:135], v[128:131], v[172:175], v[132:135]
	v_mfma_i32_16x16x64_i8 v[124:127], v[112:115], v[186:189], v[124:127]
	v_mfma_i32_16x16x64_i8 v[120:123], v[128:131], v[186:189], v[120:123]
	v_mfma_i32_16x16x64_i8 v[108:111], v[112:115], v[194:197], v[108:111]
	v_mfma_i32_16x16x64_i8 v[104:107], v[128:131], v[194:197], v[104:107]
	v_mfma_i32_16x16x64_i8 v[100:103], v[112:115], v[206:209], v[100:103]
	v_mfma_i32_16x16x64_i8 v[96:99], v[128:131], v[206:209], v[96:99]
	v_mfma_i32_16x16x64_i8 v[138:141], v[116:119], v[182:185], v[136:139]
	v_mfma_i32_16x16x64_i8 v[134:137], v[142:145], v[182:185], v[132:135]
	v_mfma_i32_16x16x64_i8 v[124:127], v[116:119], v[190:193], v[124:127]
	v_mfma_i32_16x16x64_i8 v[120:123], v[142:145], v[190:193], v[120:123]
	v_mfma_i32_16x16x64_i8 v[108:111], v[116:119], v[198:201], v[108:111]
	v_mfma_i32_16x16x64_i8 v[104:107], v[142:145], v[198:201], v[104:107]
	v_mfma_i32_16x16x64_i8 v[100:103], v[116:119], v[210:213], v[100:103]
	v_mfma_i32_16x16x64_i8 v[96:99], v[142:145], v[210:213], v[96:99]
	s_setprio 0
	s_setprio 1
	v_mfma_i32_16x16x64_i8 v[60:63], v[146:149], v[172:175], v[60:63]
	v_mfma_i32_16x16x64_i8 v[60:63], v[150:153], v[182:185], v[60:63]
	v_mfma_i32_16x16x64_i8 v[56:59], v[154:157], v[172:175], v[56:59]
	v_mfma_i32_16x16x64_i8 v[56:59], v[168:171], v[182:185], v[56:59]
	v_mfma_i32_16x16x64_i8 v[52:55], v[146:149], v[186:189], v[52:55]
	v_mfma_i32_16x16x64_i8 v[52:55], v[150:153], v[190:193], v[52:55]
	v_mfma_i32_16x16x64_i8 v[48:51], v[154:157], v[186:189], v[48:51]
	v_mfma_i32_16x16x64_i8 v[48:51], v[168:171], v[190:193], v[48:51]
	v_mfma_i32_16x16x64_i8 v[44:47], v[146:149], v[194:197], v[44:47]
	v_mfma_i32_16x16x64_i8 v[44:47], v[150:153], v[198:201], v[44:47]
	v_mfma_i32_16x16x64_i8 v[40:43], v[154:157], v[194:197], v[40:43]
	v_mfma_i32_16x16x64_i8 v[40:43], v[168:171], v[198:201], v[40:43]
	s_setprio 2
	s_barrier
	v_mfma_i32_16x16x64_i8 v[36:39], v[146:149], v[206:209], v[36:39]
	v_mfma_i32_16x16x64_i8 v[36:39], v[150:153], v[210:213], v[36:39]
	v_mfma_i32_16x16x64_i8 v[32:35], v[154:157], v[206:209], v[32:35]
	v_mfma_i32_16x16x64_i8 v[32:35], v[168:171], v[210:213], v[32:35]
	s_setprio 0
	s_add_i32 s49, s49, s33
	s_mov_b32 m0, s49
	ds_read_b128 v[172:175], v203 offset:49152
	ds_read_b128 v[182:185], v203 offset:50176
	ds_read_b128 v[186:189], v203 offset:51200
	ds_read_b128 v[190:193], v203 offset:52224
	ds_read_b128 v[194:197], v203 offset:53248
	ds_read_b128 v[198:201], v203 offset:54272
	ds_read_b128 v[206:209], v203 offset:55296
	ds_read_b128 v[210:213], v203 offset:56320
	s_add_u32 s98, s72, s16
	s_addc_u32 s99, s73, s17
	global_load_lds_dwordx4 v160, s[98:99]
	s_add_i32 m0, s49, 0x2000
	s_add_i32 s49, s70, s33
	s_add_u32 s98, s72, s18
	s_addc_u32 s99, s73, s19
	global_load_lds_dwordx4 v160, s[98:99]
	s_mov_b32 m0, s49
	s_nop 0
	s_add_u32 s98, s72, s20
	s_addc_u32 s99, s73, s21
	global_load_lds_dwordx4 v160, s[98:99]
	s_add_i32 m0, s49, 0x2000
	s_nop 0
	s_add_u32 s98, s72, s30
	s_addc_u32 s99, s73, s31
	global_load_lds_dwordx4 v160, s[98:99]
	s_mov_b32 m0, s54
	s_nop 0
	s_add_u32 s98, s100, s16
	s_addc_u32 s99, s101, s17
	global_load_lds_dwordx4 v158, s[98:99]
	s_mov_b32 m0, s55
	s_nop 0
	s_add_u32 s98, s100, s18
	s_addc_u32 s99, s101, s19
	global_load_lds_dwordx4 v158, s[98:99]
	s_waitcnt vmcnt(8)
	s_waitcnt lgkmcnt(0)
	s_barrier
	s_setprio 1
	s_waitcnt lgkmcnt(0)
	v_mfma_i32_16x16x64_i8 v[92:95], v[112:115], v[172:175], v[92:95]
	v_mfma_i32_16x16x64_i8 v[92:95], v[116:119], v[182:185], v[92:95]
	v_mfma_i32_16x16x64_i8 v[88:91], v[142:145], v[182:185], v[88:91]
	v_mfma_i32_16x16x64_i8 v[88:91], v[128:131], v[172:175], v[88:91]
	v_mfma_i32_16x16x64_i8 v[28:31], v[146:149], v[172:175], v[28:31]
	v_mfma_i32_16x16x64_i8 v[28:31], v[150:153], v[182:185], v[28:31]
	v_mfma_i32_16x16x64_i8 v[24:27], v[168:171], v[182:185], v[24:27]
	v_mfma_i32_16x16x64_i8 v[24:27], v[154:157], v[172:175], v[24:27]
	v_mfma_i32_16x16x64_i8 v[16:19], v[154:157], v[186:189], v[16:19]
	v_mfma_i32_16x16x64_i8 v[16:19], v[168:171], v[190:193], v[16:19]
	v_mfma_i32_16x16x64_i8 v[20:23], v[150:153], v[190:193], v[20:23]
	v_mfma_i32_16x16x64_i8 v[20:23], v[146:149], v[186:189], v[20:23]
	v_mfma_i32_16x16x64_i8 v[80:83], v[128:131], v[186:189], v[80:83]
	v_mfma_i32_16x16x64_i8 v[80:83], v[142:145], v[190:193], v[80:83]
	v_mfma_i32_16x16x64_i8 v[84:87], v[116:119], v[190:193], v[84:87]
	v_mfma_i32_16x16x64_i8 v[84:87], v[112:115], v[186:189], v[84:87]
	s_setprio 0
	s_setprio 1
	v_mfma_i32_16x16x64_i8 v[76:79], v[112:115], v[194:197], v[76:79]
	v_mfma_i32_16x16x64_i8 v[76:79], v[116:119], v[198:201], v[76:79]
	v_mfma_i32_16x16x64_i8 v[72:75], v[142:145], v[198:201], v[72:75]
	v_mfma_i32_16x16x64_i8 v[72:75], v[128:131], v[194:197], v[72:75]
	v_mfma_i32_16x16x64_i8 v[12:15], v[146:149], v[194:197], v[12:15]
	v_mfma_i32_16x16x64_i8 v[12:15], v[150:153], v[198:201], v[12:15]
	v_mfma_i32_16x16x64_i8 v[8:11], v[168:171], v[198:201], v[8:11]
	v_mfma_i32_16x16x64_i8 v[8:11], v[154:157], v[194:197], v[8:11]
	v_mfma_i32_16x16x64_i8 v[0:3], v[154:157], v[206:209], v[0:3]
	v_mfma_i32_16x16x64_i8 v[0:3], v[168:171], v[210:213], v[0:3]
	v_mfma_i32_16x16x64_i8 v[4:7], v[150:153], v[210:213], v[4:7]
	v_mfma_i32_16x16x64_i8 v[4:7], v[146:149], v[206:209], v[4:7]
	s_setprio 2
	s_barrier
	v_mfma_i32_16x16x64_i8 v[64:67], v[128:131], v[206:209], v[64:67]
	v_mfma_i32_16x16x64_i8 v[64:67], v[142:145], v[210:213], v[64:67]
	v_mfma_i32_16x16x64_i8 v[68:71], v[116:119], v[210:213], v[68:71]
	v_mfma_i32_16x16x64_i8 v[68:71], v[112:115], v[206:209], v[68:71]
	s_setprio 0
	s_add_i32 s48, s48, 2
	s_add_u32 s68, s68, 0x100
	s_addc_u32 s69, s69, 0
	s_add_u32 s46, s46, 0x100
	s_addc_u32 s47, s47, 0
	s_cmp_gt_u32 s48, 29
	s_cbranch_scc0 .LBB0_1180
	s_and_b64 vcc, exec, s[34:35]
	s_cbranch_vccz .LBB0_1183
	s_barrier
